# FFN-up epilogues: row sums of squares loaded ahead of the K loop, epilogue head waits vmcnt(8) instead of draining the next tile's LDS-DMA prefetch
# speedup vs baseline: 1.0002x; 1.0002x over previous
; #define PG8_STAGE(bufoff, gbase, voff) do { _Pragma("unroll") for (int _i = 0; _i < 2; ++_i) \
;         __builtin_amdgcn_global_load_lds((const unsigned*)((const char*)(gbase) + (voff)[_i]), (LAS unsigned*)(lds + (bufoff) + ldsw + _i * 8192), 16, 0, 0); } while (0)
; #define PG8_LDA(dst, b, h) do { _Pragma("unroll") for (int m = 0; m < 4; ++m) _Pragma("unroll") for (int k = 0; k < 2; ++k) dst[m][k] = *(const LAS bf16x8*)(lds + PG8_SA(b, h) + aoff + m * 2048 + k * 1024); } while (0)
; #define PG8_LDB(dst, b, h) do { _Pragma("unroll") for (int n = 0; n < 2; ++n) _Pragma("unroll") for (int k = 0; k < 2; ++k) dst[n][k] = *(const LAS bf16x8*)(lds + PG8_SB(b, h) + boff + n * 2048 + k * 1024); } while (0)
; #define PG8_MMA(ai, bj, At, Bt) do { __builtin_amdgcn_s_setprio(1); _Pragma("unroll") for (int m = 0; m < 4; ++m) _Pragma("unroll") for (int n = 0; n < 2; ++n) _Pragma("unroll") for (int k = 0; k < 2; ++k) \
;         acc[ai][bj][m][n] = __builtin_amdgcn_mfma_f32_16x16x32_bf16(Bt[n][k], At[m][k], acc[ai][bj][m][n], 0, 0, 0); __builtin_amdgcn_s_setprio(0); } while (0)
; #define PG8_WAIT_V(n) asm volatile("s_waitcnt vmcnt(" #n ")" ::: "memory")
; #define PG8_WAIT_L(n) asm volatile("s_waitcnt lgkmcnt(" #n ")" ::: "memory")
; template <class Epi>
; DI void gemm_phase(LAS unsigned char* lds, const int wid, const Gemm g, const Order& S, const Epi& E) {
;     ...
;         const char* nA = has_next ? (const char*)(g.A + (size_t)nxt.g * g.gsA + (size_t)nxt.pm * BM * g.lda) : cA;
;         const char* nB = has_next ? (const char*)(g.Bt + (size_t)nxt.g * g.gsB + (size_t)nxt.pn * BM * g.ldb) : cB;
;         for (int t = 0; t < nt; t += 2) {
;             const bool last = (t == nt - 2);
;             const char* a1 = cA + (size_t)(t + 1) * kstep;
;             const char* a2 = last ? nA : cA + (size_t)(t + 2) * kstep; const char* b2 = last ? nB : cB + (size_t)(t + 2) * kstep;
;             const char* a3 = a2 + kstep; const char* b3 = b2 + kstep;
;             PG8_LDB(B0, 0, 0); PG8_LDB(B1, 0, 1); PG8_SCHED; PG8_LDA(At, 0, 0); PG8_STAGE(PG8_SA(1, 1), a1 + hstepA, voffA);
;             PG8_WAIT_V(8); PG8_WAIT_L(0); PG8_BAR; PG8_MMA(0, 0, At, B0); PG8_MMA(0, 1, At, B1); PG8_BAR; PG8_SCHED;
;             PG8_LDA(At, 0, 1); PG8_STAGE(PG8_SB(0, 0), b2, voffB); PG8_STAGE(PG8_SB(0, 1), b2 + hstepB, voffB); PG8_STAGE(PG8_SA(0, 0), a2, voffA);
.LBB0_227:
	s_ashr_i32 s31, s30, 31
	s_lshl_b64 s[36:37], s[30:31], 19
	s_add_u32 s36, s21, s36
	s_addc_u32 s37, s25, s37
	s_and_b64 s[38:39], s[6:7], exec
	s_cselect_b32 s31, s37, s43
	s_cselect_b32 s59, s36, s42
	s_ashr_i32 s35, s34, 31
	s_lshl_b64 s[38:39], s[34:35], 19
	s_add_u32 s38, s8, s38
	s_addc_u32 s39, s9, s39
	s_and_b64 s[46:47], s[6:7], exec
	s_cselect_b32 s35, s39, s45
	s_cselect_b32 s60, s38, s44
	s_add_u32 s42, s42, 0x40080
	s_addc_u32 s43, s43, 0
	s_add_u32 s61, s44, 0x100
	v_mov_b32_e32 v0, 0
	s_addc_u32 s62, s45, 0
	s_mov_b32 s63, -2
	s_lshl_b32 s74, s40, 8
	s_add_i32 s74, s74, s95
	v_mbcnt_lo_u32_b32 v244, -1, 0
	v_mbcnt_hi_u32_b32 v244, -1, v244
	v_and_or_b32 v244, v244, 15, s74
	v_ashrrev_i32_e32 v245, 31, v244
	v_lshl_add_u64 v[246:247], v[244:245], 2, s[12:13]
	global_load_dword v236, v[246:247], off
	global_load_dword v237, v[246:247], off offset:64
	global_load_dword v238, v[246:247], off offset:128
	global_load_dword v239, v[246:247], off offset:192
	global_load_dword v240, v[246:247], off offset:512
	global_load_dword v241, v[246:247], off offset:576
	global_load_dword v242, v[246:247], off offset:640
	global_load_dword v243, v[246:247], off offset:704
	ds_read_b128 v[164:167], v151
	ds_read_b128 v[168:171], v151 offset:1024
	ds_read_b128 v[172:175], v151 offset:2048
	ds_read_b128 v[176:179], v151 offset:3072
	ds_read_b128 v[180:183], v155
	ds_read_b128 v[184:187], v155 offset:1024
	ds_read_b128 v[188:191], v155 offset:2048
	ds_read_b128 v[192:195], v155 offset:3072
	s_add_u32 s44, s42, 0xfffc0080
	s_addc_u32 s45, s43, -1
	s_cmp_eq_u32 s63, 12
	s_cselect_b32 s47, s31, s45
	s_cselect_b32 s46, s59, s44
	s_cselect_b32 s45, s35, s62
	s_cselect_b32 s44, s60, s61
	v_lshl_add_u64 v[144:145], s[42:43], 0, v[136:137]
	s_add_i32 m0, s27, 0xc000
	ds_read_b128 v[196:199], v159
	ds_read_b128 v[200:203], v159 offset:1024
	ds_read_b128 v[204:207], v159 offset:2048
	ds_read_b128 v[208:211], v159 offset:3072
	ds_read_b128 v[216:219], v159 offset:4096
	ds_read_b128 v[220:223], v159 offset:5120
	ds_read_b128 v[224:227], v159 offset:6144
	ds_read_b128 v[228:231], v159 offset:7168
	global_load_lds_dwordx4 v[144:145], off
	v_lshl_add_u64 v[144:145], s[42:43], 0, v[138:139]
	s_add_i32 m0, s27, 0xe000
	s_nop 0
	global_load_lds_dwordx4 v[144:145], off
	s_waitcnt vmcnt(8)
	s_waitcnt lgkmcnt(0)
	s_barrier
	s_setprio 1
	s_waitcnt lgkmcnt(0)
	v_mfma_f32_16x16x32_bf16 v[124:127], v[164:167], v[196:199], 0
	v_mfma_f32_16x16x32_bf16 v[120:123], v[172:175], v[196:199], 0
	v_mfma_f32_16x16x32_bf16 v[108:111], v[164:167], v[204:207], 0
	v_mfma_f32_16x16x32_bf16 v[104:107], v[172:175], v[204:207], 0
	v_mfma_f32_16x16x32_bf16 v[92:95], v[164:167], v[216:219], 0
	v_mfma_f32_16x16x32_bf16 v[88:91], v[172:175], v[216:219], 0
	v_mfma_f32_16x16x32_bf16 v[76:79], v[164:167], v[224:227], 0
	v_mfma_f32_16x16x32_bf16 v[72:75], v[172:175], v[224:227], 0
	v_mfma_f32_16x16x32_bf16 v[124:127], v[168:171], v[200:203], v[124:127]
	v_mfma_f32_16x16x32_bf16 v[120:123], v[176:179], v[200:203], v[120:123]
	v_mfma_f32_16x16x32_bf16 v[108:111], v[168:171], v[208:211], v[108:111]
	v_mfma_f32_16x16x32_bf16 v[104:107], v[176:179], v[208:211], v[104:107]
	v_mfma_f32_16x16x32_bf16 v[92:95], v[168:171], v[220:223], v[92:95]
	v_mfma_f32_16x16x32_bf16 v[88:91], v[176:179], v[220:223], v[88:91]
	v_mfma_f32_16x16x32_bf16 v[76:79], v[168:171], v[228:231], v[76:79]
	v_mfma_f32_16x16x32_bf16 v[72:75], v[176:179], v[228:231], v[72:75]
	s_setprio 0
	s_setprio 1
	v_mfma_f32_16x16x32_bf16 v[116:119], v[180:183], v[196:199], 0
	v_mfma_f32_16x16x32_bf16 v[112:115], v[188:191], v[196:199], 0
	v_mfma_f32_16x16x32_bf16 v[100:103], v[180:183], v[204:207], 0
	v_mfma_f32_16x16x32_bf16 v[96:99], v[188:191], v[204:207], 0
	v_mfma_f32_16x16x32_bf16 v[84:87], v[180:183], v[216:219], 0
	v_mfma_f32_16x16x32_bf16 v[80:83], v[188:191], v[216:219], 0
	v_mfma_f32_16x16x32_bf16 v[68:71], v[180:183], v[224:227], 0
	v_mfma_f32_16x16x32_bf16 v[64:67], v[188:191], v[224:227], 0
	v_mfma_f32_16x16x32_bf16 v[116:119], v[184:187], v[200:203], v[116:119]
	v_mfma_f32_16x16x32_bf16 v[112:115], v[192:195], v[200:203], v[112:115]
	v_mfma_f32_16x16x32_bf16 v[100:103], v[184:187], v[208:211], v[100:103]
	v_mfma_f32_16x16x32_bf16 v[96:99], v[192:195], v[208:211], v[96:99]
	v_mfma_f32_16x16x32_bf16 v[84:87], v[184:187], v[220:223], v[84:87]
	v_mfma_f32_16x16x32_bf16 v[80:83], v[192:195], v[220:223], v[80:83]
	v_mfma_f32_16x16x32_bf16 v[68:71], v[184:187], v[228:231], v[68:71]
	v_mfma_f32_16x16x32_bf16 v[64:67], v[192:195], v[228:231], v[64:67]
	s_setprio 0
	s_barrier
	s_add_i32 s64, s56, s94
	v_lshl_add_u64 v[144:145], s[44:45], 0, v[132:133]
	s_mov_b32 m0, s64
	ds_read_b128 v[196:199], v159 offset:16384
	ds_read_b128 v[200:203], v159 offset:17408
	ds_read_b128 v[204:207], v159 offset:18432
	ds_read_b128 v[208:211], v159 offset:19456
	ds_read_b128 v[216:219], v159 offset:20480
	ds_read_b128 v[220:223], v159 offset:21504
	ds_read_b128 v[224:227], v159 offset:22528
	ds_read_b128 v[228:231], v159 offset:23552
	global_load_lds_dwordx4 v[144:145], off
	s_add_i32 m0, s64, 0x2000
	s_add_u32 s64, s44, 0x40000
	v_lshl_add_u64 v[148:149], s[44:45], 0, v[128:129]
	s_addc_u32 s65, s45, 0
	s_add_i32 s66, s57, s94
	global_load_lds_dwordx4 v[148:149], off
	v_lshl_add_u64 v[152:153], s[64:65], 0, v[132:133]
	s_mov_b32 m0, s66
	v_lshl_add_u64 v[156:157], s[46:47], 0, v[130:131]
	global_load_lds_dwordx4 v[152:153], off
	v_lshl_add_u64 v[152:153], s[64:65], 0, v[128:129]
	s_add_i32 m0, s66, 0x2000
	s_nop 0
	global_load_lds_dwordx4 v[152:153], off
	v_lshl_add_u64 v[152:153], s[46:47], 0, v[134:135]
	s_mov_b32 m0, s27
	s_nop 0
	global_load_lds_dwordx4 v[152:153], off
	s_mov_b32 m0, s41
	s_nop 0
	global_load_lds_dwordx4 v[156:157], off
	s_waitcnt vmcnt(8)
	s_waitcnt lgkmcnt(0)
	s_barrier
; #define PG8_STAGE(bufoff, gbase, voff) do { _Pragma("unroll") for (int _i = 0; _i < 2; ++_i) \
;         __builtin_amdgcn_global_load_lds((const unsigned*)((const char*)(gbase) + (voff)[_i]), (LAS unsigned*)(lds + (bufoff) + ldsw + _i * 8192), 16, 0, 0); } while (0)
; #define PG8_LDA(dst, b, h) do { _Pragma("unroll") for (int m = 0; m < 4; ++m) _Pragma("unroll") for (int k = 0; k < 2; ++k) dst[m][k] = *(const LAS bf16x8*)(lds + PG8_SA(b, h) + aoff + m * 2048 + k * 1024); } while (0)
; #define PG8_LDB(dst, b, h) do { _Pragma("unroll") for (int n = 0; n < 2; ++n) _Pragma("unroll") for (int k = 0; k < 2; ++k) dst[n][k] = *(const LAS bf16x8*)(lds + PG8_SB(b, h) + boff + n * 2048 + k * 1024); } while (0)
; #define PG8_MMA(ai, bj, At, Bt) do { __builtin_amdgcn_s_setprio(1); _Pragma("unroll") for (int m = 0; m < 4; ++m) _Pragma("unroll") for (int n = 0; n < 2; ++n) _Pragma("unroll") for (int k = 0; k < 2; ++k) \
;         acc[ai][bj][m][n] = __builtin_amdgcn_mfma_f32_16x16x32_bf16(Bt[n][k], At[m][k], acc[ai][bj][m][n], 0, 0, 0); __builtin_amdgcn_s_setprio(0); } while (0)
; #define PG8_WAIT_V(n) asm volatile("s_waitcnt vmcnt(" #n ")" ::: "memory")
; #define PG8_WAIT_L(n) asm volatile("s_waitcnt lgkmcnt(" #n ")" ::: "memory")
; #define PG8_BAR __builtin_amdgcn_s_barrier()
; #define PG8_SCHED __builtin_amdgcn_sched_barrier(0)
; template <class Epi>
; DI void gemm_phase(LAS unsigned char* lds, const int wid, const Gemm g, const Order& S, const Epi& E) {
;     ...
;             PG8_WAIT_V(8); PG8_WAIT_L(0); PG8_BAR; PG8_MMA(1, 0, At, B0); PG8_MMA(1, 1, At, B1); PG8_BAR; PG8_SCHED;
;             PG8_LDB(B0, 1, 0); PG8_LDB(B1, 1, 1); PG8_SCHED; PG8_LDA(At, 1, 0); PG8_STAGE(PG8_SA(0, 1), a2 + hstepA, voffA);
;             PG8_WAIT_V(8); PG8_WAIT_L(0); PG8_BAR; PG8_MMA(0, 0, At, B0); PG8_MMA(0, 1, At, B1); PG8_BAR; PG8_SCHED;
	s_setprio 1
	s_waitcnt lgkmcnt(0)
	v_mfma_f32_16x16x32_bf16 v[60:63], v[164:167], v[196:199], 0
	v_mfma_f32_16x16x32_bf16 v[56:59], v[172:175], v[196:199], 0
	v_mfma_f32_16x16x32_bf16 v[44:47], v[164:167], v[204:207], 0
	v_mfma_f32_16x16x32_bf16 v[40:43], v[172:175], v[204:207], 0
	v_mfma_f32_16x16x32_bf16 v[28:31], v[164:167], v[216:219], 0
	v_mfma_f32_16x16x32_bf16 v[24:27], v[172:175], v[216:219], 0
	v_mfma_f32_16x16x32_bf16 v[12:15], v[164:167], v[224:227], 0
	v_mfma_f32_16x16x32_bf16 v[8:11], v[172:175], v[224:227], 0
	v_mfma_f32_16x16x32_bf16 v[60:63], v[168:171], v[200:203], v[60:63]
	v_mfma_f32_16x16x32_bf16 v[56:59], v[176:179], v[200:203], v[56:59]
	v_mfma_f32_16x16x32_bf16 v[44:47], v[168:171], v[208:211], v[44:47]
	v_mfma_f32_16x16x32_bf16 v[40:43], v[176:179], v[208:211], v[40:43]
	v_mfma_f32_16x16x32_bf16 v[28:31], v[168:171], v[220:223], v[28:31]
	v_mfma_f32_16x16x32_bf16 v[24:27], v[176:179], v[220:223], v[24:27]
	v_mfma_f32_16x16x32_bf16 v[12:15], v[168:171], v[228:231], v[12:15]
	v_mfma_f32_16x16x32_bf16 v[8:11], v[176:179], v[228:231], v[8:11]
	s_setprio 0
	s_setprio 1
	v_mfma_f32_16x16x32_bf16 v[52:55], v[180:183], v[196:199], 0
	v_mfma_f32_16x16x32_bf16 v[48:51], v[188:191], v[196:199], 0
	v_mfma_f32_16x16x32_bf16 v[36:39], v[180:183], v[204:207], 0
	v_mfma_f32_16x16x32_bf16 v[32:35], v[188:191], v[204:207], 0
	v_mfma_f32_16x16x32_bf16 v[20:23], v[180:183], v[216:219], 0
	v_mfma_f32_16x16x32_bf16 v[16:19], v[188:191], v[216:219], 0
	v_mfma_f32_16x16x32_bf16 v[4:7], v[180:183], v[224:227], 0
	v_mfma_f32_16x16x32_bf16 v[0:3], v[188:191], v[224:227], 0
	v_mfma_f32_16x16x32_bf16 v[52:55], v[184:187], v[200:203], v[52:55]
	v_mfma_f32_16x16x32_bf16 v[48:51], v[192:195], v[200:203], v[48:51]
	v_mfma_f32_16x16x32_bf16 v[36:39], v[184:187], v[208:211], v[36:39]
	v_mfma_f32_16x16x32_bf16 v[32:35], v[192:195], v[208:211], v[32:35]
	v_mfma_f32_16x16x32_bf16 v[20:23], v[184:187], v[220:223], v[20:23]
	v_mfma_f32_16x16x32_bf16 v[16:19], v[192:195], v[220:223], v[16:19]
	v_mfma_f32_16x16x32_bf16 v[4:7], v[184:187], v[228:231], v[4:7]
	v_mfma_f32_16x16x32_bf16 v[0:3], v[192:195], v[228:231], v[0:3]
	s_setprio 0
	s_barrier
	s_add_i32 s64, 0, 0x18000
	v_add_u32_e32 v146, s64, v147
	s_add_i32 s65, 0, 0x1c000
	ds_read_b128 v[164:167], v146
	ds_read_b128 v[168:171], v146 offset:1024
	ds_read_b128 v[172:175], v146 offset:2048
	ds_read_b128 v[176:179], v146 offset:3072
	v_add_u32_e32 v146, s65, v147
	ds_read_b128 v[180:183], v146
	ds_read_b128 v[184:187], v146 offset:1024
	ds_read_b128 v[188:191], v146 offset:2048
	ds_read_b128 v[192:195], v146 offset:3072
	s_add_u32 s46, s46, 0x40000
	s_addc_u32 s47, s47, 0
	s_mov_b32 m0, s48
	v_lshl_add_u64 v[160:161], s[46:47], 0, v[134:135]
	ds_read_b128 v[196:199], v159 offset:32768
	ds_read_b128 v[200:203], v159 offset:33792
	ds_read_b128 v[204:207], v159 offset:34816
	ds_read_b128 v[208:211], v159 offset:35840
	ds_read_b128 v[216:219], v159 offset:36864
	ds_read_b128 v[220:223], v159 offset:37888
	ds_read_b128 v[224:227], v159 offset:38912
	ds_read_b128 v[228:231], v159 offset:39936
	global_load_lds_dwordx4 v[160:161], off
	v_lshl_add_u64 v[160:161], s[46:47], 0, v[130:131]
	s_mov_b32 m0, s49
	s_nop 0
	global_load_lds_dwordx4 v[160:161], off
	s_waitcnt vmcnt(8)
	s_waitcnt lgkmcnt(0)
	s_barrier
	s_setprio 1
	s_waitcnt lgkmcnt(0)
	v_mfma_f32_16x16x32_bf16 v[124:127], v[164:167], v[196:199], v[124:127]
	v_mfma_f32_16x16x32_bf16 v[120:123], v[172:175], v[196:199], v[120:123]
	v_mfma_f32_16x16x32_bf16 v[108:111], v[164:167], v[204:207], v[108:111]
	v_mfma_f32_16x16x32_bf16 v[104:107], v[172:175], v[204:207], v[104:107]
	v_mfma_f32_16x16x32_bf16 v[92:95], v[164:167], v[216:219], v[92:95]
	v_mfma_f32_16x16x32_bf16 v[88:91], v[172:175], v[216:219], v[88:91]
	v_mfma_f32_16x16x32_bf16 v[76:79], v[164:167], v[224:227], v[76:79]
	v_mfma_f32_16x16x32_bf16 v[72:75], v[172:175], v[224:227], v[72:75]
	v_mfma_f32_16x16x32_bf16 v[124:127], v[168:171], v[200:203], v[124:127]
	v_mfma_f32_16x16x32_bf16 v[120:123], v[176:179], v[200:203], v[120:123]
	v_mfma_f32_16x16x32_bf16 v[108:111], v[168:171], v[208:211], v[108:111]
	v_mfma_f32_16x16x32_bf16 v[104:107], v[176:179], v[208:211], v[104:107]
	v_mfma_f32_16x16x32_bf16 v[92:95], v[168:171], v[220:223], v[92:95]
	v_mfma_f32_16x16x32_bf16 v[88:91], v[176:179], v[220:223], v[88:91]
	v_mfma_f32_16x16x32_bf16 v[76:79], v[168:171], v[228:231], v[76:79]
	v_mfma_f32_16x16x32_bf16 v[72:75], v[176:179], v[228:231], v[72:75]
	s_setprio 0
	s_setprio 1
	v_mfma_f32_16x16x32_bf16 v[116:119], v[180:183], v[196:199], v[116:119]
	v_mfma_f32_16x16x32_bf16 v[112:115], v[188:191], v[196:199], v[112:115]
	v_mfma_f32_16x16x32_bf16 v[100:103], v[180:183], v[204:207], v[100:103]
	v_mfma_f32_16x16x32_bf16 v[96:99], v[188:191], v[204:207], v[96:99]
	v_mfma_f32_16x16x32_bf16 v[84:87], v[180:183], v[216:219], v[84:87]
	v_mfma_f32_16x16x32_bf16 v[80:83], v[188:191], v[216:219], v[80:83]
	v_mfma_f32_16x16x32_bf16 v[68:71], v[180:183], v[224:227], v[68:71]
	v_mfma_f32_16x16x32_bf16 v[64:67], v[188:191], v[224:227], v[64:67]
	v_mfma_f32_16x16x32_bf16 v[116:119], v[184:187], v[200:203], v[116:119]
	v_mfma_f32_16x16x32_bf16 v[112:115], v[192:195], v[200:203], v[112:115]
	v_mfma_f32_16x16x32_bf16 v[100:103], v[184:187], v[208:211], v[100:103]
	v_mfma_f32_16x16x32_bf16 v[96:99], v[192:195], v[208:211], v[96:99]
	v_mfma_f32_16x16x32_bf16 v[84:87], v[184:187], v[220:223], v[84:87]
	v_mfma_f32_16x16x32_bf16 v[80:83], v[192:195], v[220:223], v[80:83]
	v_mfma_f32_16x16x32_bf16 v[68:71], v[184:187], v[228:231], v[68:71]
	v_mfma_f32_16x16x32_bf16 v[64:67], v[192:195], v[228:231], v[64:67]
	s_setprio 0
	s_barrier
; #define PG8_STAGE(bufoff, gbase, voff) do { _Pragma("unroll") for (int _i = 0; _i < 2; ++_i) \
;         __builtin_amdgcn_global_load_lds((const unsigned*)((const char*)(gbase) + (voff)[_i]), (LAS unsigned*)(lds + (bufoff) + ldsw + _i * 8192), 16, 0, 0); } while (0)
; #define PG8_LDA(dst, b, h) do { _Pragma("unroll") for (int m = 0; m < 4; ++m) _Pragma("unroll") for (int k = 0; k < 2; ++k) dst[m][k] = *(const LAS bf16x8*)(lds + PG8_SA(b, h) + aoff + m * 2048 + k * 1024); } while (0)
; #define PG8_MMA(ai, bj, At, Bt) do { __builtin_amdgcn_s_setprio(1); _Pragma("unroll") for (int m = 0; m < 4; ++m) _Pragma("unroll") for (int n = 0; n < 2; ++n) _Pragma("unroll") for (int k = 0; k < 2; ++k) \
;         acc[ai][bj][m][n] = __builtin_amdgcn_mfma_f32_16x16x32_bf16(Bt[n][k], At[m][k], acc[ai][bj][m][n], 0, 0, 0); __builtin_amdgcn_s_setprio(0); } while (0)
; #define PG8_WAIT_V(n) asm volatile("s_waitcnt vmcnt(" #n ")" ::: "memory")
; #define PG8_WAIT_L(n) asm volatile("s_waitcnt lgkmcnt(" #n ")" ::: "memory")
; #define PG8_BAR __builtin_amdgcn_s_barrier()
; #define PG8_SCHED __builtin_amdgcn_sched_barrier(0)
; template <class Epi>
; DI void gemm_phase(LAS unsigned char* lds, const int wid, const Gemm g, const Order& S, const Epi& E) {
;     ...
;             PG8_LDA(At, 1, 1); PG8_STAGE(PG8_SB(1, 0), b3, voffB); PG8_STAGE(PG8_SB(1, 1), b3 + hstepB, voffB); PG8_STAGE(PG8_SA(1, 0), a3, voffA);
;             PG8_WAIT_V(8); PG8_WAIT_L(0); PG8_BAR; PG8_MMA(1, 0, At, B0); PG8_MMA(1, 1, At, B1); PG8_BAR; PG8_SCHED;
	s_add_i32 s46, s64, s94
	v_lshl_add_u64 v[144:145], v[144:145], 0, s[16:17]
	s_mov_b32 m0, s46
	ds_read_b128 v[196:199], v159 offset:49152
	ds_read_b128 v[200:203], v159 offset:50176
	ds_read_b128 v[204:207], v159 offset:51200
	ds_read_b128 v[208:211], v159 offset:52224
	ds_read_b128 v[216:219], v159 offset:53248
	ds_read_b128 v[220:223], v159 offset:54272
	ds_read_b128 v[224:227], v159 offset:55296
	ds_read_b128 v[228:231], v159 offset:56320
	global_load_lds_dwordx4 v[144:145], off
	s_add_i32 m0, s46, 0x2000
	s_add_u32 s44, s44, 0x40080
	v_lshl_add_u64 v[144:145], v[148:149], 0, s[16:17]
	s_addc_u32 s45, s45, 0
	s_add_i32 s46, s65, s94
	global_load_lds_dwordx4 v[144:145], off
	v_lshl_add_u64 v[144:145], s[44:45], 0, v[132:133]
	s_mov_b32 m0, s46
	s_nop 0
	global_load_lds_dwordx4 v[144:145], off
	v_lshl_add_u64 v[144:145], s[44:45], 0, v[128:129]
	s_add_i32 m0, s46, 0x2000
	s_nop 0
	global_load_lds_dwordx4 v[144:145], off
	v_lshl_add_u64 v[144:145], v[152:153], 0, s[16:17]
	s_mov_b32 m0, s51
	s_nop 0
	global_load_lds_dwordx4 v[144:145], off
	v_lshl_add_u64 v[144:145], v[156:157], 0, s[16:17]
	s_mov_b32 m0, s52
	s_nop 0
	global_load_lds_dwordx4 v[144:145], off
	s_waitcnt vmcnt(8)
	s_waitcnt lgkmcnt(0)
	s_barrier
	s_setprio 1
	s_waitcnt lgkmcnt(0)
	v_mfma_f32_16x16x32_bf16 v[60:63], v[164:167], v[196:199], v[60:63]
	v_mfma_f32_16x16x32_bf16 v[56:59], v[172:175], v[196:199], v[56:59]
	v_mfma_f32_16x16x32_bf16 v[44:47], v[164:167], v[204:207], v[44:47]
	v_mfma_f32_16x16x32_bf16 v[40:43], v[172:175], v[204:207], v[40:43]
	v_mfma_f32_16x16x32_bf16 v[28:31], v[164:167], v[216:219], v[28:31]
	v_mfma_f32_16x16x32_bf16 v[24:27], v[172:175], v[216:219], v[24:27]
	v_mfma_f32_16x16x32_bf16 v[12:15], v[164:167], v[224:227], v[12:15]
	v_mfma_f32_16x16x32_bf16 v[8:11], v[172:175], v[224:227], v[8:11]
	v_mfma_f32_16x16x32_bf16 v[60:63], v[168:171], v[200:203], v[60:63]
	v_mfma_f32_16x16x32_bf16 v[56:59], v[176:179], v[200:203], v[56:59]
	v_mfma_f32_16x16x32_bf16 v[44:47], v[168:171], v[208:211], v[44:47]
	v_mfma_f32_16x16x32_bf16 v[40:43], v[176:179], v[208:211], v[40:43]
	v_mfma_f32_16x16x32_bf16 v[28:31], v[168:171], v[220:223], v[28:31]
	v_mfma_f32_16x16x32_bf16 v[24:27], v[176:179], v[220:223], v[24:27]
	v_mfma_f32_16x16x32_bf16 v[12:15], v[168:171], v[228:231], v[12:15]
	v_mfma_f32_16x16x32_bf16 v[8:11], v[176:179], v[228:231], v[8:11]
	s_setprio 0
	s_setprio 1
	v_mfma_f32_16x16x32_bf16 v[52:55], v[180:183], v[196:199], v[52:55]
	v_mfma_f32_16x16x32_bf16 v[48:51], v[188:191], v[196:199], v[48:51]
	v_mfma_f32_16x16x32_bf16 v[36:39], v[180:183], v[204:207], v[36:39]
	v_mfma_f32_16x16x32_bf16 v[32:35], v[188:191], v[204:207], v[32:35]
	v_mfma_f32_16x16x32_bf16 v[20:23], v[180:183], v[216:219], v[20:23]
	v_mfma_f32_16x16x32_bf16 v[16:19], v[188:191], v[216:219], v[16:19]
	v_mfma_f32_16x16x32_bf16 v[4:7], v[180:183], v[224:227], v[4:7]
	v_mfma_f32_16x16x32_bf16 v[0:3], v[188:191], v[224:227], v[0:3]
	v_mfma_f32_16x16x32_bf16 v[52:55], v[184:187], v[200:203], v[52:55]
	v_mfma_f32_16x16x32_bf16 v[48:51], v[192:195], v[200:203], v[48:51]
	v_mfma_f32_16x16x32_bf16 v[36:39], v[184:187], v[208:211], v[36:39]
	v_mfma_f32_16x16x32_bf16 v[32:35], v[192:195], v[208:211], v[32:35]
	v_mfma_f32_16x16x32_bf16 v[20:23], v[184:187], v[220:223], v[20:23]
	v_mfma_f32_16x16x32_bf16 v[16:19], v[192:195], v[220:223], v[16:19]
	v_mfma_f32_16x16x32_bf16 v[4:7], v[184:187], v[228:231], v[4:7]
	v_mfma_f32_16x16x32_bf16 v[0:3], v[192:195], v[228:231], v[0:3]
	s_setprio 0
	s_barrier
	s_add_i32 s63, s63, 2
	s_add_u32 s42, s42, 0x100
	s_addc_u32 s43, s43, 0
	s_add_u32 s61, s61, 0x100
	s_addc_u32 s62, s62, 0
	s_cmp_gt_u32 s63, 13
	s_cbranch_scc0 .LBB0_228
	s_branch .Lpeel_exit_0

; DI float silu(float x) { return x * sigm(x); }
; DI u32x4 pack8(f32x4 a, f32x4 b) { u32x4 w; w.x = pk2(a[0], a[1]); w.y = pk2(a[2], a[3]); w.z = pk2(b[0], b[1]); w.w = pk2(b[2], b[3]); return w; }
; #define EPI_ROWS(ai, m) _Pragma("unroll") for (int ai = 0; ai < 2; ++ai) _Pragma("unroll") for (int m = 0; m < 4; ++m)
; #define EPI_RSTD8(rr, ssqp, invn) float rr[2][4]; EPI_ROWS(ai, m) rr[ai][m] = (ssqp)[epi_row(u, ai, wr, m, fr)]; EPI_FENCE(); EPI_ROWS(ai, m) rr[ai][m] = rstd_of(rr[ai][m], invn);
; DI float rstd_of(float ssq, float invn) { return __builtin_amdgcn_rsqf(ssq * invn + EPS); }
;     DI void operator()(const Acc& acc, const Unit& u, int wr, int wc, int fr, int fq) const {
;         const int cb = u.pn * 128 + wc * 32 + 8 * fq;
;         EPI_RSTD8(rr, ssq, 1.0f / D)
;         EPI_ROWS(ai, m) { const int row = epi_row(u, ai, wr, m, fr); const float r = rr[ai][m];
;             f32x4 v[2];
; #pragma unroll
;             for (int n = 0; n < 2; ++n)
; #pragma unroll
;                 for (int j = 0; j < 4; ++j) v[n][j] = silu(acc[ai][0][m][n][j] * r) * (acc[ai][1][m][n][j] * r);
;             *(u32x4*)(act + (size_t)row * FF + cb) = pack8(v[0], v[1]); }
.LBB0_231:
	s_lshl_b32 s31, s40, 8
	s_add_i32 s31, s31, s95
	v_mbcnt_lo_u32_b32 v146, -1, 0
	v_mbcnt_hi_u32_b32 v146, -1, v146
	s_andn2_b64 vcc, exec, s[6:7]
	v_and_or_b32 v170, v146, 15, s31
	v_ashrrev_i32_e32 v171, 31, v170
	v_or_b32_e32 v168, 16, v170
	v_ashrrev_i32_e32 v169, 31, v168
	v_or_b32_e32 v164, 32, v170
	v_or_b32_e32 v160, 48, v170
	v_add_u32_e32 v156, 0x80, v170
	v_add_u32_e32 v152, 0x90, v170
	v_add_u32_e32 v148, 0xa0, v170
	v_add_u32_e32 v144, 0xb0, v170
	v_ashrrev_i32_e32 v165, 31, v164
	v_ashrrev_i32_e32 v161, 31, v160
	v_ashrrev_i32_e32 v157, 31, v156
	v_ashrrev_i32_e32 v153, 31, v152
	v_ashrrev_i32_e32 v149, 31, v148
	v_ashrrev_i32_e32 v145, 31, v144
	s_lshl_b32 s31, s58, 7
	v_ashrrev_i32_e32 v146, 1, v146
	s_or_b32 s31, s31, s22
	v_and_b32_e32 v146, -8, v146
	v_add_u32_e32 v172, s31, v146
	v_ashrrev_i32_e32 v173, 31, v172
	s_mov_b64 s[6:7], -1
	s_waitcnt vmcnt(8)
	v_fmamk_f32 v146, v236, 0x3a800000, v163
	v_rsq_f32_e32 v174, v146
	v_fmamk_f32 v145, v237, 0x3a800000, v163
	v_fmamk_f32 v146, v238, 0x3a800000, v163
	v_fmamk_f32 v149, v239, 0x3a800000, v163
	v_fmamk_f32 v150, v240, 0x3a800000, v163
	v_fmamk_f32 v153, v241, 0x3a800000, v163
	v_fmamk_f32 v157, v242, 0x3a800000, v163
	v_fmamk_f32 v161, v243, 0x3a800000, v163
	v_pk_mul_f32 v[124:125], v[124:125], v[174:175] op_sel_hi:[1,0]
	v_pk_mul_f32 v[126:127], v[126:127], v[174:175] op_sel_hi:[1,0]
	v_pk_mul_f32 v[120:121], v[120:121], v[174:175] op_sel_hi:[1,0]
	v_rsq_f32_e32 v176, v145
	v_rsq_f32_e32 v166, v146
	v_rsq_f32_e32 v162, v149
	v_rsq_f32_e32 v158, v150
	v_rsq_f32_e32 v154, v153
	v_rsq_f32_e32 v150, v157
	v_rsq_f32_e32 v146, v161
	v_pk_mul_f32 v[122:123], v[122:123], v[174:175] op_sel_hi:[1,0]
	v_mul_f32_e32 v145, 0xbfb8aa3b, v124
	v_mul_f32_e32 v149, 0xbfb8aa3b, v125
	v_mul_f32_e32 v153, 0xbfb8aa3b, v126
	v_mul_f32_e32 v157, 0xbfb8aa3b, v127
	v_mul_f32_e32 v161, 0xbfb8aa3b, v120
	v_mul_f32_e32 v165, 0xbfb8aa3b, v121
	v_mul_f32_e32 v167, 0xbfb8aa3b, v122
	v_mul_f32_e32 v169, 0xbfb8aa3b, v123
	v_exp_f32_e32 v145, v145
	v_exp_f32_e32 v149, v149
	v_exp_f32_e32 v153, v153
	v_exp_f32_e32 v157, v157
	v_exp_f32_e32 v161, v161
	v_exp_f32_e32 v165, v165
	v_exp_f32_e32 v167, v167
	v_exp_f32_e32 v169, v169
	v_add_f32_e32 v145, 1.0, v145
	v_add_f32_e32 v149, 1.0, v149
	v_add_f32_e32 v153, 1.0, v153
	v_add_f32_e32 v157, 1.0, v157
	v_add_f32_e32 v161, 1.0, v161
	v_add_f32_e32 v165, 1.0, v165
	v_add_f32_e32 v167, 1.0, v167
	v_add_f32_e32 v169, 1.0, v169
	v_rcp_f32_e32 v178, v145
	v_rcp_f32_e32 v179, v149
	v_rcp_f32_e32 v180, v153
	v_rcp_f32_e32 v181, v157
	v_rcp_f32_e32 v182, v161
	v_rcp_f32_e32 v183, v165
	v_rcp_f32_e32 v184, v167
	v_rcp_f32_e32 v185, v169
	v_pk_mul_f32 v[116:117], v[116:117], v[174:175] op_sel_hi:[1,0]
	v_pk_mul_f32 v[118:119], v[118:119], v[174:175] op_sel_hi:[1,0]
	v_pk_mul_f32 v[112:113], v[112:113], v[174:175] op_sel_hi:[1,0]
	v_pk_mul_f32 v[124:125], v[124:125], v[178:179]
	v_pk_mul_f32 v[126:127], v[126:127], v[180:181]
	v_pk_mul_f32 v[120:121], v[120:121], v[182:183]
	v_pk_mul_f32 v[116:117], v[116:117], v[124:125]
	v_pk_mul_f32 v[118:119], v[118:119], v[126:127]
	v_pk_mul_f32 v[112:113], v[112:113], v[120:121]
	v_pk_mul_f32 v[120:121], v[122:123], v[184:185]
	v_pk_mul_f32 v[114:115], v[114:115], v[174:175] op_sel_hi:[1,0]
	v_cvt_pk_bf16_f32 v116, v116, v117
	v_pk_mul_f32 v[114:115], v[114:115], v[120:121]
	v_cvt_pk_bf16_f32 v117, v118, v119
	v_cvt_pk_bf16_f32 v118, v112, v113
	v_mov_b64_e32 v[112:113], s[14:15]
	v_cvt_pk_bf16_f32 v119, v114, v115
	v_mad_i64_i32 v[120:121], s[42:43], v170, s55, v[112:113]
	v_lshlrev_b64 v[114:115], 1, v[172:173]
	v_pk_mul_f32 v[108:109], v[108:109], v[176:177] op_sel_hi:[1,0]
	v_lshl_add_u64 v[120:121], v[120:121], 0, v[114:115]
	v_mul_f32_e32 v122, 0xbfb8aa3b, v108
	v_mul_f32_e32 v123, 0xbfb8aa3b, v109
	v_pk_mul_f32 v[110:111], v[110:111], v[176:177] op_sel_hi:[1,0]
	v_exp_f32_e32 v122, v122
	v_exp_f32_e32 v123, v123
	global_store_dwordx4 v[120:121], v[116:119], off
	v_pk_mul_f32 v[100:101], v[100:101], v[176:177] op_sel_hi:[1,0]
	v_pk_mul_f32 v[104:105], v[104:105], v[176:177] op_sel_hi:[1,0]
	v_mul_f32_e32 v118, 0xbfb8aa3b, v110
	v_mul_f32_e32 v119, 0xbfb8aa3b, v111
	v_exp_f32_e32 v118, v118
	v_exp_f32_e32 v119, v119
	v_add_f32_e32 v116, 1.0, v122
	v_add_f32_e32 v117, 1.0, v123
	v_rcp_f32_e32 v116, v116
	v_rcp_f32_e32 v117, v117
	v_add_f32_e32 v118, 1.0, v118
	v_add_f32_e32 v119, 1.0, v119
	v_rcp_f32_e32 v118, v118
	v_rcp_f32_e32 v119, v119
	v_pk_mul_f32 v[108:109], v[108:109], v[116:117]
	v_pk_mul_f32 v[102:103], v[102:103], v[176:177] op_sel_hi:[1,0]
	v_pk_mul_f32 v[100:101], v[100:101], v[108:109]
	v_pk_mul_f32 v[108:109], v[110:111], v[118:119]
	v_mul_f32_e32 v110, 0xbfb8aa3b, v104
	v_mul_f32_e32 v111, 0xbfb8aa3b, v105
	v_exp_f32_e32 v110, v110
	v_exp_f32_e32 v111, v111
	v_pk_mul_f32 v[106:107], v[106:107], v[176:177] op_sel_hi:[1,0]
	v_pk_mul_f32 v[102:103], v[102:103], v[108:109]
	v_add_f32_e32 v108, 1.0, v110
	v_add_f32_e32 v109, 1.0, v111
	v_mul_f32_e32 v110, 0xbfb8aa3b, v106
	v_mul_f32_e32 v111, 0xbfb8aa3b, v107
	v_exp_f32_e32 v110, v110
	v_exp_f32_e32 v111, v111
	v_rcp_f32_e32 v108, v108
	v_rcp_f32_e32 v109, v109
	v_add_f32_e32 v110, 1.0, v110
	v_add_f32_e32 v111, 1.0, v111
	v_rcp_f32_e32 v110, v110
	v_rcp_f32_e32 v111, v111
	v_pk_mul_f32 v[104:105], v[104:105], v[108:109]
	v_pk_mul_f32 v[96:97], v[96:97], v[176:177] op_sel_hi:[1,0]
	v_pk_mul_f32 v[98:99], v[98:99], v[176:177] op_sel_hi:[1,0]
	v_pk_mul_f32 v[104:105], v[96:97], v[104:105]
	v_pk_mul_f32 v[96:97], v[106:107], v[110:111]
	v_pk_mul_f32 v[92:93], v[92:93], v[166:167] op_sel_hi:[1,0]
	v_pk_mul_f32 v[106:107], v[98:99], v[96:97]
; DI float silu(float x) { return x * sigm(x); }
; DI u32x4 pack8(f32x4 a, f32x4 b) { u32x4 w; w.x = pk2(a[0], a[1]); w.y = pk2(a[2], a[3]); w.z = pk2(b[0], b[1]); w.w = pk2(b[2], b[3]); return w; }
; #define EPI_ROWS(ai, m) _Pragma("unroll") for (int ai = 0; ai < 2; ++ai) _Pragma("unroll") for (int m = 0; m < 4; ++m)
;     DI void operator()(const Acc& acc, const Unit& u, int wr, int wc, int fr, int fq) const {
;     ...
;         EPI_ROWS(ai, m) { const int row = epi_row(u, ai, wr, m, fr); const float r = rr[ai][m];
;             f32x4 v[2];
; #pragma unroll
;             for (int n = 0; n < 2; ++n)
; #pragma unroll
;                 for (int j = 0; j < 4; ++j) v[n][j] = silu(acc[ai][0][m][n][j] * r) * (acc[ai][1][m][n][j] * r);
;             *(u32x4*)(act + (size_t)row * FF + cb) = pack8(v[0], v[1]); }
	v_cvt_pk_bf16_f32 v96, v100, v101
	v_mad_i64_i32 v[100:101], s[42:43], v168, s55, v[112:113]
	v_cvt_pk_bf16_f32 v97, v102, v103
	v_cvt_pk_bf16_f32 v98, v104, v105
	v_cvt_pk_bf16_f32 v99, v106, v107
	v_lshl_add_u64 v[100:101], v[100:101], 0, v[114:115]
	v_mul_f32_e32 v102, 0xbfb8aa3b, v92
	v_mul_f32_e32 v103, 0xbfb8aa3b, v93
	v_pk_mul_f32 v[94:95], v[94:95], v[166:167] op_sel_hi:[1,0]
	v_exp_f32_e32 v102, v102
	v_exp_f32_e32 v103, v103
	global_store_dwordx4 v[100:101], v[96:99], off
	v_pk_mul_f32 v[84:85], v[84:85], v[166:167] op_sel_hi:[1,0]
	v_pk_mul_f32 v[88:89], v[88:89], v[166:167] op_sel_hi:[1,0]
	v_mul_f32_e32 v98, 0xbfb8aa3b, v94
	v_mul_f32_e32 v99, 0xbfb8aa3b, v95
	v_exp_f32_e32 v98, v98
	v_exp_f32_e32 v99, v99
	v_add_f32_e32 v96, 1.0, v102
	v_add_f32_e32 v97, 1.0, v103
	v_rcp_f32_e32 v96, v96
	v_rcp_f32_e32 v97, v97
	v_add_f32_e32 v98, 1.0, v98
	v_add_f32_e32 v99, 1.0, v99
	v_rcp_f32_e32 v98, v98
	v_rcp_f32_e32 v99, v99
	v_pk_mul_f32 v[92:93], v[92:93], v[96:97]
	v_pk_mul_f32 v[86:87], v[86:87], v[166:167] op_sel_hi:[1,0]
	v_pk_mul_f32 v[84:85], v[84:85], v[92:93]
	v_pk_mul_f32 v[92:93], v[94:95], v[98:99]
	v_mul_f32_e32 v94, 0xbfb8aa3b, v88
	v_mul_f32_e32 v95, 0xbfb8aa3b, v89
	v_exp_f32_e32 v94, v94
	v_exp_f32_e32 v95, v95
	v_pk_mul_f32 v[90:91], v[90:91], v[166:167] op_sel_hi:[1,0]
	v_pk_mul_f32 v[86:87], v[86:87], v[92:93]
	v_add_f32_e32 v92, 1.0, v94
	v_add_f32_e32 v93, 1.0, v95
	v_mul_f32_e32 v94, 0xbfb8aa3b, v90
	v_mul_f32_e32 v95, 0xbfb8aa3b, v91
	v_exp_f32_e32 v94, v94
	v_exp_f32_e32 v95, v95
	v_rcp_f32_e32 v92, v92
	v_rcp_f32_e32 v93, v93
	v_add_f32_e32 v94, 1.0, v94
	v_add_f32_e32 v95, 1.0, v95
	v_rcp_f32_e32 v94, v94
	v_rcp_f32_e32 v95, v95
	v_pk_mul_f32 v[88:89], v[88:89], v[92:93]
	v_pk_mul_f32 v[80:81], v[80:81], v[166:167] op_sel_hi:[1,0]
	v_pk_mul_f32 v[82:83], v[82:83], v[166:167] op_sel_hi:[1,0]
	v_pk_mul_f32 v[88:89], v[80:81], v[88:89]
	v_pk_mul_f32 v[80:81], v[90:91], v[94:95]
	v_pk_mul_f32 v[76:77], v[76:77], v[162:163] op_sel_hi:[1,0]
	v_pk_mul_f32 v[90:91], v[82:83], v[80:81]
	v_cvt_pk_bf16_f32 v80, v84, v85
	v_mad_i64_i32 v[84:85], s[42:43], v164, s55, v[112:113]
	v_cvt_pk_bf16_f32 v81, v86, v87
	v_cvt_pk_bf16_f32 v82, v88, v89
	v_cvt_pk_bf16_f32 v83, v90, v91
	v_lshl_add_u64 v[84:85], v[84:85], 0, v[114:115]
	v_mul_f32_e32 v86, 0xbfb8aa3b, v76
	v_mul_f32_e32 v87, 0xbfb8aa3b, v77
	v_pk_mul_f32 v[78:79], v[78:79], v[162:163] op_sel_hi:[1,0]
	v_exp_f32_e32 v86, v86
	v_exp_f32_e32 v87, v87
	global_store_dwordx4 v[84:85], v[80:83], off
	v_pk_mul_f32 v[68:69], v[68:69], v[162:163] op_sel_hi:[1,0]
	v_pk_mul_f32 v[72:73], v[72:73], v[162:163] op_sel_hi:[1,0]
	v_mul_f32_e32 v82, 0xbfb8aa3b, v78
	v_mul_f32_e32 v83, 0xbfb8aa3b, v79
	v_exp_f32_e32 v82, v82
	v_exp_f32_e32 v83, v83
	v_add_f32_e32 v80, 1.0, v86
	v_add_f32_e32 v81, 1.0, v87
	v_rcp_f32_e32 v80, v80
	v_rcp_f32_e32 v81, v81
	v_add_f32_e32 v82, 1.0, v82
	v_add_f32_e32 v83, 1.0, v83
	v_rcp_f32_e32 v82, v82
	v_rcp_f32_e32 v83, v83
	v_pk_mul_f32 v[76:77], v[76:77], v[80:81]
	v_pk_mul_f32 v[70:71], v[70:71], v[162:163] op_sel_hi:[1,0]
	v_pk_mul_f32 v[68:69], v[68:69], v[76:77]
	v_pk_mul_f32 v[76:77], v[78:79], v[82:83]
	v_mul_f32_e32 v78, 0xbfb8aa3b, v72
	v_mul_f32_e32 v79, 0xbfb8aa3b, v73
	v_exp_f32_e32 v78, v78
	v_exp_f32_e32 v79, v79
	v_pk_mul_f32 v[74:75], v[74:75], v[162:163] op_sel_hi:[1,0]
	v_pk_mul_f32 v[70:71], v[70:71], v[76:77]
	v_add_f32_e32 v76, 1.0, v78
	v_add_f32_e32 v77, 1.0, v79
	v_mul_f32_e32 v78, 0xbfb8aa3b, v74
	v_mul_f32_e32 v79, 0xbfb8aa3b, v75
	v_exp_f32_e32 v78, v78
	v_exp_f32_e32 v79, v79
	v_rcp_f32_e32 v76, v76
	v_rcp_f32_e32 v77, v77
	v_add_f32_e32 v78, 1.0, v78
	v_add_f32_e32 v79, 1.0, v79
	v_rcp_f32_e32 v78, v78
	v_rcp_f32_e32 v79, v79
	v_pk_mul_f32 v[72:73], v[72:73], v[76:77]
	v_pk_mul_f32 v[64:65], v[64:65], v[162:163] op_sel_hi:[1,0]
	v_pk_mul_f32 v[66:67], v[66:67], v[162:163] op_sel_hi:[1,0]
	v_pk_mul_f32 v[72:73], v[64:65], v[72:73]
	v_pk_mul_f32 v[64:65], v[74:75], v[78:79]
	v_pk_mul_f32 v[60:61], v[60:61], v[158:159] op_sel_hi:[1,0]
	v_pk_mul_f32 v[74:75], v[66:67], v[64:65]
	v_cvt_pk_bf16_f32 v64, v68, v69
	v_mad_i64_i32 v[68:69], s[42:43], v160, s55, v[112:113]
	v_cvt_pk_bf16_f32 v65, v70, v71
	v_cvt_pk_bf16_f32 v66, v72, v73
	v_cvt_pk_bf16_f32 v67, v74, v75
	v_lshl_add_u64 v[68:69], v[68:69], 0, v[114:115]
	v_mul_f32_e32 v70, 0xbfb8aa3b, v60
	v_mul_f32_e32 v71, 0xbfb8aa3b, v61
	v_pk_mul_f32 v[62:63], v[62:63], v[158:159] op_sel_hi:[1,0]
	v_exp_f32_e32 v70, v70
	v_exp_f32_e32 v71, v71
	global_store_dwordx4 v[68:69], v[64:67], off
	v_pk_mul_f32 v[52:53], v[52:53], v[158:159] op_sel_hi:[1,0]
	v_pk_mul_f32 v[56:57], v[56:57], v[158:159] op_sel_hi:[1,0]
	v_mul_f32_e32 v66, 0xbfb8aa3b, v62
	v_mul_f32_e32 v67, 0xbfb8aa3b, v63
	v_exp_f32_e32 v66, v66
	v_exp_f32_e32 v67, v67
	v_add_f32_e32 v64, 1.0, v70
	v_add_f32_e32 v65, 1.0, v71
	v_rcp_f32_e32 v64, v64
	v_rcp_f32_e32 v65, v65
	v_add_f32_e32 v66, 1.0, v66
	v_add_f32_e32 v67, 1.0, v67
	v_rcp_f32_e32 v66, v66
	v_rcp_f32_e32 v67, v67
	v_pk_mul_f32 v[60:61], v[60:61], v[64:65]
	v_pk_mul_f32 v[54:55], v[54:55], v[158:159] op_sel_hi:[1,0]
	v_pk_mul_f32 v[52:53], v[52:53], v[60:61]
	v_pk_mul_f32 v[60:61], v[62:63], v[66:67]
	v_mul_f32_e32 v62, 0xbfb8aa3b, v56
	v_mul_f32_e32 v63, 0xbfb8aa3b, v57
	v_exp_f32_e32 v62, v62
	v_exp_f32_e32 v63, v63
	v_pk_mul_f32 v[58:59], v[58:59], v[158:159] op_sel_hi:[1,0]
	v_pk_mul_f32 v[54:55], v[54:55], v[60:61]
	v_add_f32_e32 v60, 1.0, v62
	v_add_f32_e32 v61, 1.0, v63
	v_mul_f32_e32 v62, 0xbfb8aa3b, v58
	v_mul_f32_e32 v63, 0xbfb8aa3b, v59
	v_exp_f32_e32 v62, v62
	v_exp_f32_e32 v63, v63
	v_rcp_f32_e32 v60, v60
	v_rcp_f32_e32 v61, v61
; DI float silu(float x) { return x * sigm(x); }
; DI int lane_id() { int l; asm volatile("v_mbcnt_lo_u32_b32 %0, -1, 0\n\tv_mbcnt_hi_u32_b32 %0, -1, %0" : "=v"(l)); return l; }
; DI u32x4 pack8(f32x4 a, f32x4 b) { u32x4 w; w.x = pk2(a[0], a[1]); w.y = pk2(a[2], a[3]); w.z = pk2(b[0], b[1]); w.w = pk2(b[2], b[3]); return w; }
; #define PG8_BAR __builtin_amdgcn_s_barrier()
; #define EPI_ROWS(ai, m) _Pragma("unroll") for (int ai = 0; ai < 2; ++ai) _Pragma("unroll") for (int m = 0; m < 4; ++m)
; template <class Epi>
; DI void gemm_phase(LAS unsigned char* lds, const int wid, const Gemm g, const Order& S, const Epi& E) {
;     ...
;         if (wr == 0) PG8_BAR;
;         { const int le = lane_id(); E(acc, cur, wr, wc, le & 15, le >> 4); }
;         if (!has_next) break;
; #pragma unroll
;         for (int a = 0; a < 2; ++a)
; #pragma unroll
;             for (int b = 0; b < 2; ++b)
; #pragma unroll
;                 for (int m = 0; m < 4; ++m)
; #pragma unroll
;                     for (int n = 0; n < 2; ++n) acc[a][b][m][n] = (f32x4){0.f, 0.f, 0.f, 0.f};
;         cur = nxt; cA = nA; cB = nB; ++ui;
;         if (wr == 1) PG8_BAR;
;     DI void operator()(const Acc& acc, const Unit& u, int wr, int wc, int fr, int fq) const {
;     ...
;         EPI_ROWS(ai, m) { const int row = epi_row(u, ai, wr, m, fr); const float r = rr[ai][m];
;             f32x4 v[2];
; #pragma unroll
;             for (int n = 0; n < 2; ++n)
; #pragma unroll
;                 for (int j = 0; j < 4; ++j) v[n][j] = silu(acc[ai][0][m][n][j] * r) * (acc[ai][1][m][n][j] * r);
;             *(u32x4*)(act + (size_t)row * FF + cb) = pack8(v[0], v[1]); }
	v_add_f32_e32 v62, 1.0, v62
	v_add_f32_e32 v63, 1.0, v63
	v_rcp_f32_e32 v62, v62
	v_rcp_f32_e32 v63, v63
	v_pk_mul_f32 v[56:57], v[56:57], v[60:61]
	v_pk_mul_f32 v[48:49], v[48:49], v[158:159] op_sel_hi:[1,0]
	v_pk_mul_f32 v[50:51], v[50:51], v[158:159] op_sel_hi:[1,0]
	v_pk_mul_f32 v[56:57], v[48:49], v[56:57]
	v_pk_mul_f32 v[48:49], v[58:59], v[62:63]
	v_pk_mul_f32 v[44:45], v[44:45], v[154:155] op_sel_hi:[1,0]
	v_pk_mul_f32 v[58:59], v[50:51], v[48:49]
	v_cvt_pk_bf16_f32 v48, v52, v53
	v_mad_i64_i32 v[52:53], s[42:43], v156, s55, v[112:113]
	v_cvt_pk_bf16_f32 v49, v54, v55
	v_cvt_pk_bf16_f32 v50, v56, v57
	v_cvt_pk_bf16_f32 v51, v58, v59
	v_lshl_add_u64 v[52:53], v[52:53], 0, v[114:115]
	v_mul_f32_e32 v54, 0xbfb8aa3b, v44
	v_mul_f32_e32 v55, 0xbfb8aa3b, v45
	v_pk_mul_f32 v[46:47], v[46:47], v[154:155] op_sel_hi:[1,0]
	v_exp_f32_e32 v54, v54
	v_exp_f32_e32 v55, v55
	global_store_dwordx4 v[52:53], v[48:51], off
	v_pk_mul_f32 v[36:37], v[36:37], v[154:155] op_sel_hi:[1,0]
	v_pk_mul_f32 v[40:41], v[40:41], v[154:155] op_sel_hi:[1,0]
	v_mul_f32_e32 v50, 0xbfb8aa3b, v46
	v_mul_f32_e32 v51, 0xbfb8aa3b, v47
	v_exp_f32_e32 v50, v50
	v_exp_f32_e32 v51, v51
	v_add_f32_e32 v48, 1.0, v54
	v_add_f32_e32 v49, 1.0, v55
	v_rcp_f32_e32 v48, v48
	v_rcp_f32_e32 v49, v49
	v_add_f32_e32 v50, 1.0, v50
	v_add_f32_e32 v51, 1.0, v51
	v_rcp_f32_e32 v50, v50
	v_rcp_f32_e32 v51, v51
	v_pk_mul_f32 v[44:45], v[44:45], v[48:49]
	v_pk_mul_f32 v[38:39], v[38:39], v[154:155] op_sel_hi:[1,0]
	v_pk_mul_f32 v[36:37], v[36:37], v[44:45]
	v_pk_mul_f32 v[44:45], v[46:47], v[50:51]
	v_mul_f32_e32 v46, 0xbfb8aa3b, v40
	v_mul_f32_e32 v47, 0xbfb8aa3b, v41
	v_exp_f32_e32 v46, v46
	v_exp_f32_e32 v47, v47
	v_pk_mul_f32 v[42:43], v[42:43], v[154:155] op_sel_hi:[1,0]
	v_pk_mul_f32 v[38:39], v[38:39], v[44:45]
	v_add_f32_e32 v44, 1.0, v46
	v_add_f32_e32 v45, 1.0, v47
	v_mul_f32_e32 v46, 0xbfb8aa3b, v42
	v_mul_f32_e32 v47, 0xbfb8aa3b, v43
	v_exp_f32_e32 v46, v46
	v_exp_f32_e32 v47, v47
	v_rcp_f32_e32 v44, v44
	v_rcp_f32_e32 v45, v45
	v_add_f32_e32 v46, 1.0, v46
	v_add_f32_e32 v47, 1.0, v47
	v_rcp_f32_e32 v46, v46
	v_rcp_f32_e32 v47, v47
	v_pk_mul_f32 v[40:41], v[40:41], v[44:45]
	v_pk_mul_f32 v[32:33], v[32:33], v[154:155] op_sel_hi:[1,0]
	v_pk_mul_f32 v[34:35], v[34:35], v[154:155] op_sel_hi:[1,0]
	v_pk_mul_f32 v[40:41], v[32:33], v[40:41]
	v_pk_mul_f32 v[32:33], v[42:43], v[46:47]
	v_pk_mul_f32 v[28:29], v[28:29], v[150:151] op_sel_hi:[1,0]
	v_pk_mul_f32 v[42:43], v[34:35], v[32:33]
	v_cvt_pk_bf16_f32 v32, v36, v37
	v_mad_i64_i32 v[36:37], s[42:43], v152, s55, v[112:113]
	v_cvt_pk_bf16_f32 v33, v38, v39
	v_cvt_pk_bf16_f32 v34, v40, v41
	v_cvt_pk_bf16_f32 v35, v42, v43
	v_lshl_add_u64 v[36:37], v[36:37], 0, v[114:115]
	v_mul_f32_e32 v38, 0xbfb8aa3b, v28
	v_mul_f32_e32 v39, 0xbfb8aa3b, v29
	v_pk_mul_f32 v[30:31], v[30:31], v[150:151] op_sel_hi:[1,0]
	v_exp_f32_e32 v38, v38
	v_exp_f32_e32 v39, v39
	global_store_dwordx4 v[36:37], v[32:35], off
	v_pk_mul_f32 v[20:21], v[20:21], v[150:151] op_sel_hi:[1,0]
	v_pk_mul_f32 v[24:25], v[24:25], v[150:151] op_sel_hi:[1,0]
	v_mul_f32_e32 v34, 0xbfb8aa3b, v30
	v_mul_f32_e32 v35, 0xbfb8aa3b, v31
	v_exp_f32_e32 v34, v34
	v_exp_f32_e32 v35, v35
	v_add_f32_e32 v32, 1.0, v38
	v_add_f32_e32 v33, 1.0, v39
	v_rcp_f32_e32 v32, v32
	v_rcp_f32_e32 v33, v33
	v_add_f32_e32 v34, 1.0, v34
	v_add_f32_e32 v35, 1.0, v35
	v_rcp_f32_e32 v34, v34
	v_rcp_f32_e32 v35, v35
	v_pk_mul_f32 v[28:29], v[28:29], v[32:33]
	v_pk_mul_f32 v[22:23], v[22:23], v[150:151] op_sel_hi:[1,0]
	v_pk_mul_f32 v[20:21], v[20:21], v[28:29]
	v_pk_mul_f32 v[28:29], v[30:31], v[34:35]
	v_mul_f32_e32 v30, 0xbfb8aa3b, v24
	v_mul_f32_e32 v31, 0xbfb8aa3b, v25
	v_exp_f32_e32 v30, v30
	v_exp_f32_e32 v31, v31
	v_pk_mul_f32 v[26:27], v[26:27], v[150:151] op_sel_hi:[1,0]
	v_pk_mul_f32 v[22:23], v[22:23], v[28:29]
	v_add_f32_e32 v28, 1.0, v30
	v_add_f32_e32 v29, 1.0, v31
	v_mul_f32_e32 v30, 0xbfb8aa3b, v26
	v_mul_f32_e32 v31, 0xbfb8aa3b, v27
	v_exp_f32_e32 v30, v30
	v_exp_f32_e32 v31, v31
	v_rcp_f32_e32 v28, v28
	v_rcp_f32_e32 v29, v29
	v_add_f32_e32 v30, 1.0, v30
	v_add_f32_e32 v31, 1.0, v31
	v_rcp_f32_e32 v30, v30
	v_rcp_f32_e32 v31, v31
	v_pk_mul_f32 v[24:25], v[24:25], v[28:29]
	v_pk_mul_f32 v[16:17], v[16:17], v[150:151] op_sel_hi:[1,0]
	v_pk_mul_f32 v[18:19], v[18:19], v[150:151] op_sel_hi:[1,0]
	v_pk_mul_f32 v[24:25], v[16:17], v[24:25]
	v_pk_mul_f32 v[16:17], v[26:27], v[30:31]
	v_pk_mul_f32 v[12:13], v[12:13], v[146:147] op_sel_hi:[1,0]
	v_pk_mul_f32 v[26:27], v[18:19], v[16:17]
	v_cvt_pk_bf16_f32 v16, v20, v21
	v_mad_i64_i32 v[20:21], s[42:43], v148, s55, v[112:113]
	v_cvt_pk_bf16_f32 v17, v22, v23
	v_cvt_pk_bf16_f32 v18, v24, v25
	v_cvt_pk_bf16_f32 v19, v26, v27
	v_lshl_add_u64 v[20:21], v[20:21], 0, v[114:115]
	v_mul_f32_e32 v22, 0xbfb8aa3b, v12
	v_mul_f32_e32 v23, 0xbfb8aa3b, v13
	v_pk_mul_f32 v[14:15], v[14:15], v[146:147] op_sel_hi:[1,0]
	v_exp_f32_e32 v22, v22
	v_exp_f32_e32 v23, v23
	global_store_dwordx4 v[20:21], v[16:19], off
	v_pk_mul_f32 v[4:5], v[4:5], v[146:147] op_sel_hi:[1,0]
	v_pk_mul_f32 v[8:9], v[8:9], v[146:147] op_sel_hi:[1,0]
	v_mul_f32_e32 v18, 0xbfb8aa3b, v14
	v_mul_f32_e32 v19, 0xbfb8aa3b, v15
	v_exp_f32_e32 v18, v18
	v_exp_f32_e32 v19, v19
	v_add_f32_e32 v16, 1.0, v22
	v_add_f32_e32 v17, 1.0, v23
	v_rcp_f32_e32 v16, v16
	v_rcp_f32_e32 v17, v17
	v_add_f32_e32 v18, 1.0, v18
	v_add_f32_e32 v19, 1.0, v19
	v_rcp_f32_e32 v18, v18
	v_rcp_f32_e32 v19, v19
	v_pk_mul_f32 v[12:13], v[12:13], v[16:17]
	v_pk_mul_f32 v[6:7], v[6:7], v[146:147] op_sel_hi:[1,0]
	v_pk_mul_f32 v[4:5], v[4:5], v[12:13]
	v_pk_mul_f32 v[12:13], v[14:15], v[18:19]
	v_mul_f32_e32 v14, 0xbfb8aa3b, v8
	v_mul_f32_e32 v15, 0xbfb8aa3b, v9
	v_exp_f32_e32 v14, v14
	v_exp_f32_e32 v15, v15
	v_pk_mul_f32 v[10:11], v[10:11], v[146:147] op_sel_hi:[1,0]
	v_pk_mul_f32 v[6:7], v[6:7], v[12:13]
	v_add_f32_e32 v12, 1.0, v14
	v_add_f32_e32 v13, 1.0, v15
	v_mul_f32_e32 v14, 0xbfb8aa3b, v10
	v_mul_f32_e32 v15, 0xbfb8aa3b, v11
	v_exp_f32_e32 v14, v14
	v_exp_f32_e32 v15, v15
	v_rcp_f32_e32 v12, v12
	v_rcp_f32_e32 v13, v13
	v_add_f32_e32 v14, 1.0, v14
	v_add_f32_e32 v15, 1.0, v15
	v_rcp_f32_e32 v14, v14
	v_rcp_f32_e32 v15, v15
	v_pk_mul_f32 v[8:9], v[8:9], v[12:13]
	v_pk_mul_f32 v[0:1], v[0:1], v[146:147] op_sel_hi:[1,0]
	v_pk_mul_f32 v[2:3], v[2:3], v[146:147] op_sel_hi:[1,0]
	v_pk_mul_f32 v[8:9], v[0:1], v[8:9]
	v_pk_mul_f32 v[0:1], v[10:11], v[14:15]
	s_nop 0
	v_pk_mul_f32 v[10:11], v[2:3], v[0:1]
	v_cvt_pk_bf16_f32 v0, v4, v5
	v_mad_i64_i32 v[4:5], s[42:43], v144, s55, v[112:113]
	v_cvt_pk_bf16_f32 v1, v6, v7
	v_cvt_pk_bf16_f32 v2, v8, v9
	v_cvt_pk_bf16_f32 v3, v10, v11
	v_lshl_add_u64 v[4:5], v[4:5], 0, v[114:115]
	global_store_dwordx4 v[4:5], v[0:3], off
	s_cbranch_vccnz .LBB0_224
	s_andn2_b64 vcc, exec, s[10:11]
	s_cbranch_vccnz .LBB0_223
	s_barrier
	s_branch .LBB0_223

; #define PG8_STAGE(bufoff, gbase, voff) do { _Pragma("unroll") for (int _i = 0; _i < 2; ++_i) \
;         __builtin_amdgcn_global_load_lds((const unsigned*)((const char*)(gbase) + (voff)[_i]), (LAS unsigned*)(lds + (bufoff) + ldsw + _i * 8192), 16, 0, 0); } while (0)
; #define PG8_LDA(dst, b, h) do { _Pragma("unroll") for (int m = 0; m < 4; ++m) _Pragma("unroll") for (int k = 0; k < 2; ++k) dst[m][k] = *(const LAS bf16x8*)(lds + PG8_SA(b, h) + aoff + m * 2048 + k * 1024); } while (0)
; #define PG8_LDB(dst, b, h) do { _Pragma("unroll") for (int n = 0; n < 2; ++n) _Pragma("unroll") for (int k = 0; k < 2; ++k) dst[n][k] = *(const LAS bf16x8*)(lds + PG8_SB(b, h) + boff + n * 2048 + k * 1024); } while (0)
; #define PG8_MMA(ai, bj, At, Bt) do { __builtin_amdgcn_s_setprio(1); _Pragma("unroll") for (int m = 0; m < 4; ++m) _Pragma("unroll") for (int n = 0; n < 2; ++n) _Pragma("unroll") for (int k = 0; k < 2; ++k) \
;         acc[ai][bj][m][n] = __builtin_amdgcn_mfma_f32_16x16x32_bf16(Bt[n][k], At[m][k], acc[ai][bj][m][n], 0, 0, 0); __builtin_amdgcn_s_setprio(0); } while (0)
; template <class Epi>
; DI void gemm_phase(LAS unsigned char* lds, const int wid, const Gemm g, const Order& S, const Epi& E) {
;     ...
;         const bool has_next = S.next(ui + 1, nxt);
;         const char* nA = has_next ? (const char*)(g.A + (size_t)nxt.g * g.gsA + (size_t)nxt.pm * BM * g.lda) : cA;
;         const char* nB = has_next ? (const char*)(g.Bt + (size_t)nxt.g * g.gsB + (size_t)nxt.pn * BM * g.ldb) : cB;
;         for (int t = 0; t < nt; t += 2) {
;             const bool last = (t == nt - 2);
;             const char* a1 = cA + (size_t)(t + 1) * kstep;
;             const char* a2 = last ? nA : cA + (size_t)(t + 2) * kstep; const char* b2 = last ? nB : cB + (size_t)(t + 2) * kstep;
;             const char* a3 = a2 + kstep; const char* b3 = b2 + kstep;
;             PG8_LDB(B0, 0, 0); PG8_LDB(B1, 0, 1); PG8_SCHED; PG8_LDA(At, 0, 0); PG8_STAGE(PG8_SA(1, 1), a1 + hstepA, voffA);
;             PG8_WAIT_V(8); PG8_WAIT_L(0); PG8_BAR; PG8_MMA(0, 0, At, B0); PG8_MMA(0, 1, At, B1); PG8_BAR; PG8_SCHED;
;             PG8_LDA(At, 0, 1); PG8_STAGE(PG8_SB(0, 0), b2, voffB); PG8_STAGE(PG8_SB(0, 1), b2 + hstepB, voffB); PG8_STAGE(PG8_SA(0, 0), a2, voffA);
;             PG8_WAIT_V(8); PG8_WAIT_L(0); PG8_BAR; PG8_MMA(1, 0, At, B0); PG8_MMA(1, 1, At, B1); PG8_BAR; PG8_SCHED;
.LBB0_1335:
	s_ashr_i32 s27, s26, 31
	s_lshl_b64 s[30:31], s[26:27], 19
	s_add_u32 s30, s6, s30
	s_addc_u32 s31, s7, s31
	s_and_b64 s[34:35], s[8:9], exec
	s_cselect_b32 s27, s31, s39
	s_cselect_b32 s56, s30, s38
	s_ashr_i32 s29, s28, 31
	s_lshl_b64 s[34:35], s[28:29], 19
	s_add_u32 s34, s21, s34
	s_addc_u32 s35, s44, s35
	s_and_b64 s[42:43], s[8:9], exec
	s_cselect_b32 s29, s35, s41
	s_cselect_b32 s57, s34, s40
	s_add_u32 s38, s38, 0x40080
	s_addc_u32 s39, s39, 0
	s_add_u32 s58, s40, 0x100
	v_mov_b32_e32 v0, 0
	s_addc_u32 s59, s41, 0
	s_mov_b32 s60, -2
	s_lshl_b32 s65, s36, 8
	s_add_i32 s65, s65, s95
	v_mbcnt_lo_u32_b32 v244, -1, 0
	v_mbcnt_hi_u32_b32 v244, -1, v244
	v_and_or_b32 v244, v244, 15, s65
	v_ashrrev_i32_e32 v245, 31, v244
	v_lshl_add_u64 v[246:247], v[244:245], 2, s[12:13]
	global_load_dword v236, v[246:247], off
	global_load_dword v237, v[246:247], off offset:64
	global_load_dword v238, v[246:247], off offset:128
	global_load_dword v239, v[246:247], off offset:192
	global_load_dword v240, v[246:247], off offset:512
	global_load_dword v241, v[246:247], off offset:576
	global_load_dword v242, v[246:247], off offset:640
	global_load_dword v243, v[246:247], off offset:704
	ds_read_b128 v[164:167], v151
	ds_read_b128 v[168:171], v151 offset:1024
	ds_read_b128 v[172:175], v151 offset:2048
	ds_read_b128 v[176:179], v151 offset:3072
	ds_read_b128 v[180:183], v155
	ds_read_b128 v[184:187], v155 offset:1024
	ds_read_b128 v[188:191], v155 offset:2048
	ds_read_b128 v[192:195], v155 offset:3072
	s_add_u32 s40, s38, 0xfffc0080
	s_addc_u32 s41, s39, -1
	s_cmp_eq_u32 s60, 12
	s_cselect_b32 s43, s27, s41
	s_cselect_b32 s42, s56, s40
	s_cselect_b32 s41, s29, s59
	s_cselect_b32 s40, s57, s58
	v_lshl_add_u64 v[144:145], s[38:39], 0, v[136:137]
	s_add_i32 m0, s37, 0xc000
	ds_read_b128 v[196:199], v159
	ds_read_b128 v[200:203], v159 offset:1024
	ds_read_b128 v[204:207], v159 offset:2048
	ds_read_b128 v[208:211], v159 offset:3072
	ds_read_b128 v[212:215], v159 offset:4096
	ds_read_b128 v[216:219], v159 offset:5120
	ds_read_b128 v[220:223], v159 offset:6144
	ds_read_b128 v[224:227], v159 offset:7168
	global_load_lds_dwordx4 v[144:145], off
	v_lshl_add_u64 v[144:145], s[38:39], 0, v[138:139]
	s_add_i32 m0, s37, 0xe000
	s_nop 0
	global_load_lds_dwordx4 v[144:145], off
	s_waitcnt vmcnt(8)
	s_waitcnt lgkmcnt(0)
	s_barrier
	s_setprio 1
	s_waitcnt lgkmcnt(0)
	v_mfma_f32_16x16x32_bf16 v[124:127], v[164:167], v[196:199], 0
	v_mfma_f32_16x16x32_bf16 v[120:123], v[172:175], v[196:199], 0
	v_mfma_f32_16x16x32_bf16 v[108:111], v[164:167], v[204:207], 0
	v_mfma_f32_16x16x32_bf16 v[104:107], v[172:175], v[204:207], 0
	v_mfma_f32_16x16x32_bf16 v[92:95], v[164:167], v[212:215], 0
	v_mfma_f32_16x16x32_bf16 v[88:91], v[172:175], v[212:215], 0
	v_mfma_f32_16x16x32_bf16 v[76:79], v[164:167], v[220:223], 0
	v_mfma_f32_16x16x32_bf16 v[72:75], v[172:175], v[220:223], 0
	v_mfma_f32_16x16x32_bf16 v[124:127], v[168:171], v[200:203], v[124:127]
	v_mfma_f32_16x16x32_bf16 v[120:123], v[176:179], v[200:203], v[120:123]
	v_mfma_f32_16x16x32_bf16 v[108:111], v[168:171], v[208:211], v[108:111]
	v_mfma_f32_16x16x32_bf16 v[104:107], v[176:179], v[208:211], v[104:107]
	v_mfma_f32_16x16x32_bf16 v[92:95], v[168:171], v[216:219], v[92:95]
	v_mfma_f32_16x16x32_bf16 v[88:91], v[176:179], v[216:219], v[88:91]
	v_mfma_f32_16x16x32_bf16 v[76:79], v[168:171], v[224:227], v[76:79]
	v_mfma_f32_16x16x32_bf16 v[72:75], v[176:179], v[224:227], v[72:75]
	s_setprio 0
	s_setprio 1
	v_mfma_f32_16x16x32_bf16 v[116:119], v[180:183], v[196:199], 0
	v_mfma_f32_16x16x32_bf16 v[112:115], v[188:191], v[196:199], 0
	v_mfma_f32_16x16x32_bf16 v[100:103], v[180:183], v[204:207], 0
	v_mfma_f32_16x16x32_bf16 v[96:99], v[188:191], v[204:207], 0
	v_mfma_f32_16x16x32_bf16 v[84:87], v[180:183], v[212:215], 0
	v_mfma_f32_16x16x32_bf16 v[80:83], v[188:191], v[212:215], 0
	v_mfma_f32_16x16x32_bf16 v[68:71], v[180:183], v[220:223], 0
	v_mfma_f32_16x16x32_bf16 v[64:67], v[188:191], v[220:223], 0
	v_mfma_f32_16x16x32_bf16 v[116:119], v[184:187], v[200:203], v[116:119]
	v_mfma_f32_16x16x32_bf16 v[112:115], v[192:195], v[200:203], v[112:115]
	v_mfma_f32_16x16x32_bf16 v[100:103], v[184:187], v[208:211], v[100:103]
	v_mfma_f32_16x16x32_bf16 v[96:99], v[192:195], v[208:211], v[96:99]
	v_mfma_f32_16x16x32_bf16 v[84:87], v[184:187], v[216:219], v[84:87]
	v_mfma_f32_16x16x32_bf16 v[80:83], v[192:195], v[216:219], v[80:83]
	v_mfma_f32_16x16x32_bf16 v[68:71], v[184:187], v[224:227], v[68:71]
	v_mfma_f32_16x16x32_bf16 v[64:67], v[192:195], v[224:227], v[64:67]
	s_setprio 0
	s_barrier
	s_add_i32 s61, s53, s94
	v_lshl_add_u64 v[144:145], s[40:41], 0, v[132:133]
	s_mov_b32 m0, s61
	ds_read_b128 v[196:199], v159 offset:16384
	ds_read_b128 v[200:203], v159 offset:17408
	ds_read_b128 v[204:207], v159 offset:18432
	ds_read_b128 v[208:211], v159 offset:19456
	ds_read_b128 v[212:215], v159 offset:20480
	ds_read_b128 v[216:219], v159 offset:21504
	ds_read_b128 v[220:223], v159 offset:22528
	ds_read_b128 v[224:227], v159 offset:23552
	global_load_lds_dwordx4 v[144:145], off
	s_add_i32 m0, s61, 0x2000
	s_add_u32 s62, s40, 0x40000
	v_lshl_add_u64 v[148:149], s[40:41], 0, v[128:129]
	s_addc_u32 s63, s41, 0
	s_add_i32 s61, s54, s94
	global_load_lds_dwordx4 v[148:149], off
	v_lshl_add_u64 v[152:153], s[62:63], 0, v[132:133]
	s_mov_b32 m0, s61
	v_lshl_add_u64 v[156:157], s[42:43], 0, v[130:131]
	global_load_lds_dwordx4 v[152:153], off
	v_lshl_add_u64 v[152:153], s[62:63], 0, v[128:129]
	s_add_i32 m0, s61, 0x2000
	s_nop 0
	global_load_lds_dwordx4 v[152:153], off
	v_lshl_add_u64 v[152:153], s[42:43], 0, v[134:135]
	s_mov_b32 m0, s37
	s_nop 0
	global_load_lds_dwordx4 v[152:153], off
	s_mov_b32 m0, s46
	s_nop 0
	global_load_lds_dwordx4 v[156:157], off
	s_waitcnt vmcnt(8)
	s_waitcnt lgkmcnt(0)
	s_barrier
; #define PG8_STAGE(bufoff, gbase, voff) do { _Pragma("unroll") for (int _i = 0; _i < 2; ++_i) \
;         __builtin_amdgcn_global_load_lds((const unsigned*)((const char*)(gbase) + (voff)[_i]), (LAS unsigned*)(lds + (bufoff) + ldsw + _i * 8192), 16, 0, 0); } while (0)
; #define PG8_LDA(dst, b, h) do { _Pragma("unroll") for (int m = 0; m < 4; ++m) _Pragma("unroll") for (int k = 0; k < 2; ++k) dst[m][k] = *(const LAS bf16x8*)(lds + PG8_SA(b, h) + aoff + m * 2048 + k * 1024); } while (0)
; #define PG8_LDB(dst, b, h) do { _Pragma("unroll") for (int n = 0; n < 2; ++n) _Pragma("unroll") for (int k = 0; k < 2; ++k) dst[n][k] = *(const LAS bf16x8*)(lds + PG8_SB(b, h) + boff + n * 2048 + k * 1024); } while (0)
; #define PG8_WAIT_V(n) asm volatile("s_waitcnt vmcnt(" #n ")" ::: "memory")
; #define PG8_BAR __builtin_amdgcn_s_barrier()
; template <class Epi>
; DI void gemm_phase(LAS unsigned char* lds, const int wid, const Gemm g, const Order& S, const Epi& E) {
;     ...
;         const bool has_next = S.next(ui + 1, nxt);
;         const char* nA = has_next ? (const char*)(g.A + (size_t)nxt.g * g.gsA + (size_t)nxt.pm * BM * g.lda) : cA;
;         const char* nB = has_next ? (const char*)(g.Bt + (size_t)nxt.g * g.gsB + (size_t)nxt.pn * BM * g.ldb) : cB;
;         for (int t = 0; t < nt; t += 2) {
;             const bool last = (t == nt - 2);
;             const char* a1 = cA + (size_t)(t + 1) * kstep;
;             const char* a2 = last ? nA : cA + (size_t)(t + 2) * kstep; const char* b2 = last ? nB : cB + (size_t)(t + 2) * kstep;
;             const char* a3 = a2 + kstep; const char* b3 = b2 + kstep;
;             PG8_LDB(B0, 0, 0); PG8_LDB(B1, 0, 1); PG8_SCHED; PG8_LDA(At, 0, 0); PG8_STAGE(PG8_SA(1, 1), a1 + hstepA, voffA);
;             PG8_WAIT_V(8); PG8_WAIT_L(0); PG8_BAR; PG8_MMA(0, 0, At, B0); PG8_MMA(0, 1, At, B1); PG8_BAR; PG8_SCHED;
;             PG8_LDA(At, 0, 1); PG8_STAGE(PG8_SB(0, 0), b2, voffB); PG8_STAGE(PG8_SB(0, 1), b2 + hstepB, voffB); PG8_STAGE(PG8_SA(0, 0), a2, voffA);
;             PG8_WAIT_V(8); PG8_WAIT_L(0); PG8_BAR; PG8_MMA(1, 0, At, B0); PG8_MMA(1, 1, At, B1); PG8_BAR; PG8_SCHED;
;             PG8_LDB(B0, 1, 0); PG8_LDB(B1, 1, 1); PG8_SCHED; PG8_LDA(At, 1, 0); PG8_STAGE(PG8_SA(0, 1), a2 + hstepA, voffA);
;             PG8_WAIT_V(8); PG8_WAIT_L(0); PG8_BAR; PG8_MMA(0, 0, At, B0); PG8_MMA(0, 1, At, B1); PG8_BAR; PG8_SCHED;
	s_setprio 1
	s_waitcnt lgkmcnt(0)
	v_mfma_f32_16x16x32_bf16 v[60:63], v[164:167], v[196:199], 0
	v_mfma_f32_16x16x32_bf16 v[56:59], v[172:175], v[196:199], 0
	v_mfma_f32_16x16x32_bf16 v[44:47], v[164:167], v[204:207], 0
	v_mfma_f32_16x16x32_bf16 v[40:43], v[172:175], v[204:207], 0
	v_mfma_f32_16x16x32_bf16 v[28:31], v[164:167], v[212:215], 0
	v_mfma_f32_16x16x32_bf16 v[24:27], v[172:175], v[212:215], 0
	v_mfma_f32_16x16x32_bf16 v[12:15], v[164:167], v[220:223], 0
	v_mfma_f32_16x16x32_bf16 v[8:11], v[172:175], v[220:223], 0
	v_mfma_f32_16x16x32_bf16 v[60:63], v[168:171], v[200:203], v[60:63]
	v_mfma_f32_16x16x32_bf16 v[56:59], v[176:179], v[200:203], v[56:59]
	v_mfma_f32_16x16x32_bf16 v[44:47], v[168:171], v[208:211], v[44:47]
	v_mfma_f32_16x16x32_bf16 v[40:43], v[176:179], v[208:211], v[40:43]
	v_mfma_f32_16x16x32_bf16 v[28:31], v[168:171], v[216:219], v[28:31]
	v_mfma_f32_16x16x32_bf16 v[24:27], v[176:179], v[216:219], v[24:27]
	v_mfma_f32_16x16x32_bf16 v[12:15], v[168:171], v[224:227], v[12:15]
	v_mfma_f32_16x16x32_bf16 v[8:11], v[176:179], v[224:227], v[8:11]
	s_setprio 0
	s_setprio 1
	v_mfma_f32_16x16x32_bf16 v[52:55], v[180:183], v[196:199], 0
	v_mfma_f32_16x16x32_bf16 v[48:51], v[188:191], v[196:199], 0
	v_mfma_f32_16x16x32_bf16 v[36:39], v[180:183], v[204:207], 0
	v_mfma_f32_16x16x32_bf16 v[32:35], v[188:191], v[204:207], 0
	v_mfma_f32_16x16x32_bf16 v[20:23], v[180:183], v[212:215], 0
	v_mfma_f32_16x16x32_bf16 v[16:19], v[188:191], v[212:215], 0
	v_mfma_f32_16x16x32_bf16 v[4:7], v[180:183], v[220:223], 0
	v_mfma_f32_16x16x32_bf16 v[0:3], v[188:191], v[220:223], 0
	v_mfma_f32_16x16x32_bf16 v[52:55], v[184:187], v[200:203], v[52:55]
	v_mfma_f32_16x16x32_bf16 v[48:51], v[192:195], v[200:203], v[48:51]
	v_mfma_f32_16x16x32_bf16 v[36:39], v[184:187], v[208:211], v[36:39]
	v_mfma_f32_16x16x32_bf16 v[32:35], v[192:195], v[208:211], v[32:35]
	v_mfma_f32_16x16x32_bf16 v[20:23], v[184:187], v[216:219], v[20:23]
	v_mfma_f32_16x16x32_bf16 v[16:19], v[192:195], v[216:219], v[16:19]
	v_mfma_f32_16x16x32_bf16 v[4:7], v[184:187], v[224:227], v[4:7]
	v_mfma_f32_16x16x32_bf16 v[0:3], v[192:195], v[224:227], v[0:3]
	s_setprio 0
	s_barrier
	s_add_i32 s61, 0, 0x18000
	v_add_u32_e32 v146, s61, v147
	s_add_i32 s62, 0, 0x1c000
	ds_read_b128 v[164:167], v146
	ds_read_b128 v[168:171], v146 offset:1024
	ds_read_b128 v[172:175], v146 offset:2048
	ds_read_b128 v[176:179], v146 offset:3072
	v_add_u32_e32 v146, s62, v147
	ds_read_b128 v[180:183], v146
	ds_read_b128 v[184:187], v146 offset:1024
	ds_read_b128 v[188:191], v146 offset:2048
	ds_read_b128 v[192:195], v146 offset:3072
	s_add_u32 s42, s42, 0x40000
	s_addc_u32 s43, s43, 0
	s_mov_b32 m0, s47
	v_lshl_add_u64 v[160:161], s[42:43], 0, v[134:135]
	ds_read_b128 v[196:199], v159 offset:32768
	ds_read_b128 v[200:203], v159 offset:33792
	ds_read_b128 v[204:207], v159 offset:34816
	ds_read_b128 v[208:211], v159 offset:35840
	ds_read_b128 v[212:215], v159 offset:36864
	ds_read_b128 v[216:219], v159 offset:37888
	ds_read_b128 v[220:223], v159 offset:38912
	ds_read_b128 v[224:227], v159 offset:39936
	global_load_lds_dwordx4 v[160:161], off
	v_lshl_add_u64 v[160:161], s[42:43], 0, v[130:131]
	s_mov_b32 m0, s48
	s_nop 0
	global_load_lds_dwordx4 v[160:161], off
	s_waitcnt vmcnt(8)
	s_waitcnt lgkmcnt(0)
	s_barrier
	s_setprio 1
	s_waitcnt lgkmcnt(0)
	v_mfma_f32_16x16x32_bf16 v[124:127], v[164:167], v[196:199], v[124:127]
	v_mfma_f32_16x16x32_bf16 v[120:123], v[172:175], v[196:199], v[120:123]
	v_mfma_f32_16x16x32_bf16 v[108:111], v[164:167], v[204:207], v[108:111]
	v_mfma_f32_16x16x32_bf16 v[104:107], v[172:175], v[204:207], v[104:107]
	v_mfma_f32_16x16x32_bf16 v[92:95], v[164:167], v[212:215], v[92:95]
	v_mfma_f32_16x16x32_bf16 v[88:91], v[172:175], v[212:215], v[88:91]
	v_mfma_f32_16x16x32_bf16 v[76:79], v[164:167], v[220:223], v[76:79]
	v_mfma_f32_16x16x32_bf16 v[72:75], v[172:175], v[220:223], v[72:75]
	v_mfma_f32_16x16x32_bf16 v[124:127], v[168:171], v[200:203], v[124:127]
	v_mfma_f32_16x16x32_bf16 v[120:123], v[176:179], v[200:203], v[120:123]
	v_mfma_f32_16x16x32_bf16 v[108:111], v[168:171], v[208:211], v[108:111]
	v_mfma_f32_16x16x32_bf16 v[104:107], v[176:179], v[208:211], v[104:107]
	v_mfma_f32_16x16x32_bf16 v[92:95], v[168:171], v[216:219], v[92:95]
	v_mfma_f32_16x16x32_bf16 v[88:91], v[176:179], v[216:219], v[88:91]
	v_mfma_f32_16x16x32_bf16 v[76:79], v[168:171], v[224:227], v[76:79]
	v_mfma_f32_16x16x32_bf16 v[72:75], v[176:179], v[224:227], v[72:75]
	s_setprio 0
	s_setprio 1
	v_mfma_f32_16x16x32_bf16 v[116:119], v[180:183], v[196:199], v[116:119]
	v_mfma_f32_16x16x32_bf16 v[112:115], v[188:191], v[196:199], v[112:115]
	v_mfma_f32_16x16x32_bf16 v[100:103], v[180:183], v[204:207], v[100:103]
	v_mfma_f32_16x16x32_bf16 v[96:99], v[188:191], v[204:207], v[96:99]
	v_mfma_f32_16x16x32_bf16 v[84:87], v[180:183], v[212:215], v[84:87]
	v_mfma_f32_16x16x32_bf16 v[80:83], v[188:191], v[212:215], v[80:83]
	v_mfma_f32_16x16x32_bf16 v[68:71], v[180:183], v[220:223], v[68:71]
	v_mfma_f32_16x16x32_bf16 v[64:67], v[188:191], v[220:223], v[64:67]
	v_mfma_f32_16x16x32_bf16 v[116:119], v[184:187], v[200:203], v[116:119]
	v_mfma_f32_16x16x32_bf16 v[112:115], v[192:195], v[200:203], v[112:115]
	v_mfma_f32_16x16x32_bf16 v[100:103], v[184:187], v[208:211], v[100:103]
	v_mfma_f32_16x16x32_bf16 v[96:99], v[192:195], v[208:211], v[96:99]
	v_mfma_f32_16x16x32_bf16 v[84:87], v[184:187], v[216:219], v[84:87]
	v_mfma_f32_16x16x32_bf16 v[80:83], v[192:195], v[216:219], v[80:83]
	v_mfma_f32_16x16x32_bf16 v[68:71], v[184:187], v[224:227], v[68:71]
	v_mfma_f32_16x16x32_bf16 v[64:67], v[192:195], v[224:227], v[64:67]
	s_setprio 0
	s_barrier
; #define PG8_STAGE(bufoff, gbase, voff) do { _Pragma("unroll") for (int _i = 0; _i < 2; ++_i) \
;         __builtin_amdgcn_global_load_lds((const unsigned*)((const char*)(gbase) + (voff)[_i]), (LAS unsigned*)(lds + (bufoff) + ldsw + _i * 8192), 16, 0, 0); } while (0)
; #define PG8_LDA(dst, b, h) do { _Pragma("unroll") for (int m = 0; m < 4; ++m) _Pragma("unroll") for (int k = 0; k < 2; ++k) dst[m][k] = *(const LAS bf16x8*)(lds + PG8_SA(b, h) + aoff + m * 2048 + k * 1024); } while (0)
; #define PG8_LDB(dst, b, h) do { _Pragma("unroll") for (int n = 0; n < 2; ++n) _Pragma("unroll") for (int k = 0; k < 2; ++k) dst[n][k] = *(const LAS bf16x8*)(lds + PG8_SB(b, h) + boff + n * 2048 + k * 1024); } while (0)
; #define PG8_WAIT_V(n) asm volatile("s_waitcnt vmcnt(" #n ")" ::: "memory")
; #define PG8_WAIT_L(n) asm volatile("s_waitcnt lgkmcnt(" #n ")" ::: "memory")
; template <class Epi>
; DI void gemm_phase(LAS unsigned char* lds, const int wid, const Gemm g, const Order& S, const Epi& E) {
;     ...
;         for (int t = 0; t < nt; t += 2) {
;             const bool last = (t == nt - 2);
;             const char* a1 = cA + (size_t)(t + 1) * kstep;
;             const char* a2 = last ? nA : cA + (size_t)(t + 2) * kstep; const char* b2 = last ? nB : cB + (size_t)(t + 2) * kstep;
;             const char* a3 = a2 + kstep; const char* b3 = b2 + kstep;
;             PG8_LDB(B0, 0, 0); PG8_LDB(B1, 0, 1); PG8_SCHED; PG8_LDA(At, 0, 0); PG8_STAGE(PG8_SA(1, 1), a1 + hstepA, voffA);
;             PG8_WAIT_V(8); PG8_WAIT_L(0); PG8_BAR; PG8_MMA(0, 0, At, B0); PG8_MMA(0, 1, At, B1); PG8_BAR; PG8_SCHED;
;             PG8_LDA(At, 0, 1); PG8_STAGE(PG8_SB(0, 0), b2, voffB); PG8_STAGE(PG8_SB(0, 1), b2 + hstepB, voffB); PG8_STAGE(PG8_SA(0, 0), a2, voffA);
;             PG8_WAIT_V(8); PG8_WAIT_L(0); PG8_BAR; PG8_MMA(1, 0, At, B0); PG8_MMA(1, 1, At, B1); PG8_BAR; PG8_SCHED;
;             PG8_LDB(B0, 1, 0); PG8_LDB(B1, 1, 1); PG8_SCHED; PG8_LDA(At, 1, 0); PG8_STAGE(PG8_SA(0, 1), a2 + hstepA, voffA);
;             PG8_WAIT_V(8); PG8_WAIT_L(0); PG8_BAR; PG8_MMA(0, 0, At, B0); PG8_MMA(0, 1, At, B1); PG8_BAR; PG8_SCHED;
;             PG8_LDA(At, 1, 1); PG8_STAGE(PG8_SB(1, 0), b3, voffB); PG8_STAGE(PG8_SB(1, 1), b3 + hstepB, voffB); PG8_STAGE(PG8_SA(1, 0), a3, voffA);
;             PG8_WAIT_V(8); PG8_WAIT_L(0); PG8_BAR; PG8_MMA(1, 0, At, B0); PG8_MMA(1, 1, At, B1); PG8_BAR; PG8_SCHED;
	s_add_i32 s42, s61, s94
	v_lshl_add_u64 v[144:145], v[144:145], 0, s[16:17]
	s_mov_b32 m0, s42
	ds_read_b128 v[196:199], v159 offset:49152
	ds_read_b128 v[200:203], v159 offset:50176
	ds_read_b128 v[204:207], v159 offset:51200
	ds_read_b128 v[208:211], v159 offset:52224
	ds_read_b128 v[212:215], v159 offset:53248
	ds_read_b128 v[216:219], v159 offset:54272
	ds_read_b128 v[220:223], v159 offset:55296
	ds_read_b128 v[224:227], v159 offset:56320
	global_load_lds_dwordx4 v[144:145], off
	s_add_i32 m0, s42, 0x2000
	s_add_u32 s40, s40, 0x40080
	v_lshl_add_u64 v[144:145], v[148:149], 0, s[16:17]
	s_addc_u32 s41, s41, 0
	s_add_i32 s42, s62, s94
	global_load_lds_dwordx4 v[144:145], off
	v_lshl_add_u64 v[144:145], s[40:41], 0, v[132:133]
	s_mov_b32 m0, s42
	s_nop 0
	global_load_lds_dwordx4 v[144:145], off
	v_lshl_add_u64 v[144:145], s[40:41], 0, v[128:129]
	s_add_i32 m0, s42, 0x2000
	s_nop 0
	global_load_lds_dwordx4 v[144:145], off
	v_lshl_add_u64 v[144:145], v[152:153], 0, s[16:17]
	s_mov_b32 m0, s51
	s_nop 0
	global_load_lds_dwordx4 v[144:145], off
	v_lshl_add_u64 v[144:145], v[156:157], 0, s[16:17]
	s_mov_b32 m0, s52
	s_nop 0
	global_load_lds_dwordx4 v[144:145], off
	s_waitcnt vmcnt(8)
	s_waitcnt lgkmcnt(0)
	s_barrier
	s_setprio 1
	s_waitcnt lgkmcnt(0)
	v_mfma_f32_16x16x32_bf16 v[60:63], v[164:167], v[196:199], v[60:63]
	v_mfma_f32_16x16x32_bf16 v[56:59], v[172:175], v[196:199], v[56:59]
	v_mfma_f32_16x16x32_bf16 v[44:47], v[164:167], v[204:207], v[44:47]
	v_mfma_f32_16x16x32_bf16 v[40:43], v[172:175], v[204:207], v[40:43]
	v_mfma_f32_16x16x32_bf16 v[28:31], v[164:167], v[212:215], v[28:31]
	v_mfma_f32_16x16x32_bf16 v[24:27], v[172:175], v[212:215], v[24:27]
	v_mfma_f32_16x16x32_bf16 v[12:15], v[164:167], v[220:223], v[12:15]
	v_mfma_f32_16x16x32_bf16 v[8:11], v[172:175], v[220:223], v[8:11]
	v_mfma_f32_16x16x32_bf16 v[60:63], v[168:171], v[200:203], v[60:63]
	v_mfma_f32_16x16x32_bf16 v[56:59], v[176:179], v[200:203], v[56:59]
	v_mfma_f32_16x16x32_bf16 v[44:47], v[168:171], v[208:211], v[44:47]
	v_mfma_f32_16x16x32_bf16 v[40:43], v[176:179], v[208:211], v[40:43]
	v_mfma_f32_16x16x32_bf16 v[28:31], v[168:171], v[216:219], v[28:31]
	v_mfma_f32_16x16x32_bf16 v[24:27], v[176:179], v[216:219], v[24:27]
	v_mfma_f32_16x16x32_bf16 v[12:15], v[168:171], v[224:227], v[12:15]
	v_mfma_f32_16x16x32_bf16 v[8:11], v[176:179], v[224:227], v[8:11]
	s_setprio 0
	s_setprio 1
	v_mfma_f32_16x16x32_bf16 v[52:55], v[180:183], v[196:199], v[52:55]
	v_mfma_f32_16x16x32_bf16 v[48:51], v[188:191], v[196:199], v[48:51]
	v_mfma_f32_16x16x32_bf16 v[36:39], v[180:183], v[204:207], v[36:39]
	v_mfma_f32_16x16x32_bf16 v[32:35], v[188:191], v[204:207], v[32:35]
	v_mfma_f32_16x16x32_bf16 v[20:23], v[180:183], v[212:215], v[20:23]
	v_mfma_f32_16x16x32_bf16 v[16:19], v[188:191], v[212:215], v[16:19]
	v_mfma_f32_16x16x32_bf16 v[4:7], v[180:183], v[220:223], v[4:7]
	v_mfma_f32_16x16x32_bf16 v[0:3], v[188:191], v[220:223], v[0:3]
	v_mfma_f32_16x16x32_bf16 v[52:55], v[184:187], v[200:203], v[52:55]
	v_mfma_f32_16x16x32_bf16 v[48:51], v[192:195], v[200:203], v[48:51]
	v_mfma_f32_16x16x32_bf16 v[36:39], v[184:187], v[208:211], v[36:39]
	v_mfma_f32_16x16x32_bf16 v[32:35], v[192:195], v[208:211], v[32:35]
	v_mfma_f32_16x16x32_bf16 v[20:23], v[184:187], v[216:219], v[20:23]
	v_mfma_f32_16x16x32_bf16 v[16:19], v[192:195], v[216:219], v[16:19]
	v_mfma_f32_16x16x32_bf16 v[4:7], v[184:187], v[224:227], v[4:7]
	v_mfma_f32_16x16x32_bf16 v[0:3], v[192:195], v[224:227], v[0:3]
	s_setprio 0
	s_barrier
	s_add_i32 s60, s60, 2
	s_add_u32 s38, s38, 0x100
	s_addc_u32 s39, s39, 0
	s_add_u32 s58, s58, 0x100
	s_addc_u32 s59, s59, 0
	s_cmp_gt_u32 s60, 13
	s_cbranch_scc0 .LBB0_1336
	s_branch .Lpeel_exit_9

; DI float silu(float x) { return x * sigm(x); }
; DI u32x4 pack8(f32x4 a, f32x4 b) { u32x4 w; w.x = pk2(a[0], a[1]); w.y = pk2(a[2], a[3]); w.z = pk2(b[0], b[1]); w.w = pk2(b[2], b[3]); return w; }
; #define EPI_ROWS(ai, m) _Pragma("unroll") for (int ai = 0; ai < 2; ++ai) _Pragma("unroll") for (int m = 0; m < 4; ++m)
; #define EPI_RSTD8(rr, ssqp, invn) float rr[2][4]; EPI_ROWS(ai, m) rr[ai][m] = (ssqp)[epi_row(u, ai, wr, m, fr)]; EPI_FENCE(); EPI_ROWS(ai, m) rr[ai][m] = rstd_of(rr[ai][m], invn);
; DI float rstd_of(float ssq, float invn) { return __builtin_amdgcn_rsqf(ssq * invn + EPS); }
;     DI void operator()(const Acc& acc, const Unit& u, int wr, int wc, int fr, int fq) const {
;         const int cb = u.pn * 128 + wc * 32 + 8 * fq;
;         EPI_RSTD8(rr, ssq, 1.0f / D)
;         EPI_ROWS(ai, m) { const int row = epi_row(u, ai, wr, m, fr); const float r = rr[ai][m];
;             f32x4 v[2];
; #pragma unroll
;             for (int n = 0; n < 2; ++n)
; #pragma unroll
;                 for (int j = 0; j < 4; ++j) v[n][j] = silu(acc[ai][0][m][n][j] * r) * (acc[ai][1][m][n][j] * r);
;             *(u32x4*)(act + (size_t)row * FF + cb) = pack8(v[0], v[1]); }
.LBB0_1339:
	s_lshl_b32 s27, s36, 8
	s_add_i32 s27, s27, s95
	v_mbcnt_lo_u32_b32 v146, -1, 0
	v_mbcnt_hi_u32_b32 v146, -1, v146
	s_andn2_b64 vcc, exec, s[8:9]
	v_and_or_b32 v170, v146, 15, s27
	v_ashrrev_i32_e32 v171, 31, v170
	v_or_b32_e32 v168, 16, v170
	v_ashrrev_i32_e32 v169, 31, v168
	v_or_b32_e32 v164, 32, v170
	v_or_b32_e32 v160, 48, v170
	v_add_u32_e32 v156, 0x80, v170
	v_add_u32_e32 v152, 0x90, v170
	v_add_u32_e32 v148, 0xa0, v170
	v_add_u32_e32 v144, 0xb0, v170
	v_ashrrev_i32_e32 v165, 31, v164
	v_ashrrev_i32_e32 v161, 31, v160
	v_ashrrev_i32_e32 v157, 31, v156
	v_ashrrev_i32_e32 v153, 31, v152
	v_ashrrev_i32_e32 v149, 31, v148
	v_ashrrev_i32_e32 v145, 31, v144
	s_lshl_b32 s27, s55, 7
	v_ashrrev_i32_e32 v146, 1, v146
	s_or_b32 s27, s27, s22
	v_and_b32_e32 v146, -8, v146
	v_add_u32_e32 v172, s27, v146
	v_ashrrev_i32_e32 v173, 31, v172
	s_mov_b64 s[8:9], -1
	s_waitcnt vmcnt(8)
	v_fmamk_f32 v146, v236, 0x3a800000, v163
	v_rsq_f32_e32 v174, v146
	v_fmamk_f32 v145, v237, 0x3a800000, v163
	v_fmamk_f32 v146, v238, 0x3a800000, v163
	v_fmamk_f32 v149, v239, 0x3a800000, v163
	v_fmamk_f32 v150, v240, 0x3a800000, v163
	v_fmamk_f32 v153, v241, 0x3a800000, v163
	v_fmamk_f32 v157, v242, 0x3a800000, v163
	v_fmamk_f32 v161, v243, 0x3a800000, v163
	v_pk_mul_f32 v[124:125], v[124:125], v[174:175] op_sel_hi:[1,0]
	v_pk_mul_f32 v[126:127], v[126:127], v[174:175] op_sel_hi:[1,0]
	v_pk_mul_f32 v[120:121], v[120:121], v[174:175] op_sel_hi:[1,0]
	v_rsq_f32_e32 v176, v145
	v_rsq_f32_e32 v166, v146
	v_rsq_f32_e32 v162, v149
	v_rsq_f32_e32 v158, v150
	v_rsq_f32_e32 v154, v153
	v_rsq_f32_e32 v150, v157
	v_rsq_f32_e32 v146, v161
	v_pk_mul_f32 v[122:123], v[122:123], v[174:175] op_sel_hi:[1,0]
	v_mul_f32_e32 v145, 0xbfb8aa3b, v124
	v_mul_f32_e32 v149, 0xbfb8aa3b, v125
	v_mul_f32_e32 v153, 0xbfb8aa3b, v126
	v_mul_f32_e32 v157, 0xbfb8aa3b, v127
	v_mul_f32_e32 v161, 0xbfb8aa3b, v120
	v_mul_f32_e32 v165, 0xbfb8aa3b, v121
	v_mul_f32_e32 v167, 0xbfb8aa3b, v122
	v_mul_f32_e32 v169, 0xbfb8aa3b, v123
	v_exp_f32_e32 v145, v145
	v_exp_f32_e32 v149, v149
	v_exp_f32_e32 v153, v153
	v_exp_f32_e32 v157, v157
	v_exp_f32_e32 v161, v161
	v_exp_f32_e32 v165, v165
	v_exp_f32_e32 v167, v167
	v_exp_f32_e32 v169, v169
	v_add_f32_e32 v145, 1.0, v145
	v_add_f32_e32 v149, 1.0, v149
	v_add_f32_e32 v153, 1.0, v153
	v_add_f32_e32 v157, 1.0, v157
	v_add_f32_e32 v161, 1.0, v161
	v_add_f32_e32 v165, 1.0, v165
	v_add_f32_e32 v167, 1.0, v167
	v_add_f32_e32 v169, 1.0, v169
	v_rcp_f32_e32 v178, v145
	v_rcp_f32_e32 v179, v149
	v_rcp_f32_e32 v180, v153
	v_rcp_f32_e32 v181, v157
	v_rcp_f32_e32 v182, v161
	v_rcp_f32_e32 v183, v165
	v_rcp_f32_e32 v184, v167
	v_rcp_f32_e32 v185, v169
	v_pk_mul_f32 v[116:117], v[116:117], v[174:175] op_sel_hi:[1,0]
	v_pk_mul_f32 v[118:119], v[118:119], v[174:175] op_sel_hi:[1,0]
	v_pk_mul_f32 v[112:113], v[112:113], v[174:175] op_sel_hi:[1,0]
	v_pk_mul_f32 v[124:125], v[124:125], v[178:179]
	v_pk_mul_f32 v[126:127], v[126:127], v[180:181]
	v_pk_mul_f32 v[120:121], v[120:121], v[182:183]
	v_pk_mul_f32 v[116:117], v[116:117], v[124:125]
	v_pk_mul_f32 v[118:119], v[118:119], v[126:127]
	v_pk_mul_f32 v[112:113], v[112:113], v[120:121]
	v_pk_mul_f32 v[120:121], v[122:123], v[184:185]
	v_pk_mul_f32 v[114:115], v[114:115], v[174:175] op_sel_hi:[1,0]
	v_cvt_pk_bf16_f32 v116, v116, v117
	v_pk_mul_f32 v[114:115], v[114:115], v[120:121]
	v_cvt_pk_bf16_f32 v117, v118, v119
	v_cvt_pk_bf16_f32 v118, v112, v113
	v_mov_b64_e32 v[112:113], s[14:15]
	v_cvt_pk_bf16_f32 v119, v114, v115
	v_mad_i64_i32 v[120:121], s[38:39], v170, s49, v[112:113]
	v_lshlrev_b64 v[114:115], 1, v[172:173]
	v_pk_mul_f32 v[108:109], v[108:109], v[176:177] op_sel_hi:[1,0]
	v_lshl_add_u64 v[120:121], v[120:121], 0, v[114:115]
	v_mul_f32_e32 v122, 0xbfb8aa3b, v108
	v_mul_f32_e32 v123, 0xbfb8aa3b, v109
	v_pk_mul_f32 v[110:111], v[110:111], v[176:177] op_sel_hi:[1,0]
	v_exp_f32_e32 v122, v122
	v_exp_f32_e32 v123, v123
	global_store_dwordx4 v[120:121], v[116:119], off
	v_pk_mul_f32 v[100:101], v[100:101], v[176:177] op_sel_hi:[1,0]
	v_pk_mul_f32 v[104:105], v[104:105], v[176:177] op_sel_hi:[1,0]
	v_mul_f32_e32 v118, 0xbfb8aa3b, v110
	v_mul_f32_e32 v119, 0xbfb8aa3b, v111
	v_exp_f32_e32 v118, v118
	v_exp_f32_e32 v119, v119
	v_add_f32_e32 v116, 1.0, v122
	v_add_f32_e32 v117, 1.0, v123
	v_rcp_f32_e32 v116, v116
	v_rcp_f32_e32 v117, v117
	v_add_f32_e32 v118, 1.0, v118
	v_add_f32_e32 v119, 1.0, v119
	v_rcp_f32_e32 v118, v118
	v_rcp_f32_e32 v119, v119
	v_pk_mul_f32 v[108:109], v[108:109], v[116:117]
	v_pk_mul_f32 v[102:103], v[102:103], v[176:177] op_sel_hi:[1,0]
	v_pk_mul_f32 v[100:101], v[100:101], v[108:109]
	v_pk_mul_f32 v[108:109], v[110:111], v[118:119]
	v_mul_f32_e32 v110, 0xbfb8aa3b, v104
	v_mul_f32_e32 v111, 0xbfb8aa3b, v105
	v_exp_f32_e32 v110, v110
	v_exp_f32_e32 v111, v111
	v_pk_mul_f32 v[106:107], v[106:107], v[176:177] op_sel_hi:[1,0]
	v_pk_mul_f32 v[102:103], v[102:103], v[108:109]
	v_add_f32_e32 v108, 1.0, v110
	v_add_f32_e32 v109, 1.0, v111
	v_mul_f32_e32 v110, 0xbfb8aa3b, v106
	v_mul_f32_e32 v111, 0xbfb8aa3b, v107
	v_exp_f32_e32 v110, v110
	v_exp_f32_e32 v111, v111
	v_rcp_f32_e32 v108, v108
	v_rcp_f32_e32 v109, v109
	v_add_f32_e32 v110, 1.0, v110
	v_add_f32_e32 v111, 1.0, v111
	v_rcp_f32_e32 v110, v110
	v_rcp_f32_e32 v111, v111
	v_pk_mul_f32 v[104:105], v[104:105], v[108:109]
	v_pk_mul_f32 v[96:97], v[96:97], v[176:177] op_sel_hi:[1,0]
	v_pk_mul_f32 v[98:99], v[98:99], v[176:177] op_sel_hi:[1,0]
	v_pk_mul_f32 v[104:105], v[96:97], v[104:105]
	v_pk_mul_f32 v[96:97], v[106:107], v[110:111]
	v_pk_mul_f32 v[92:93], v[92:93], v[166:167] op_sel_hi:[1,0]
	v_pk_mul_f32 v[106:107], v[98:99], v[96:97]
; DI float silu(float x) { return x * sigm(x); }
; DI u32x4 pack8(f32x4 a, f32x4 b) { u32x4 w; w.x = pk2(a[0], a[1]); w.y = pk2(a[2], a[3]); w.z = pk2(b[0], b[1]); w.w = pk2(b[2], b[3]); return w; }
; #define EPI_ROWS(ai, m) _Pragma("unroll") for (int ai = 0; ai < 2; ++ai) _Pragma("unroll") for (int m = 0; m < 4; ++m)
;     DI void operator()(const Acc& acc, const Unit& u, int wr, int wc, int fr, int fq) const {
;     ...
;         EPI_ROWS(ai, m) { const int row = epi_row(u, ai, wr, m, fr); const float r = rr[ai][m];
;             f32x4 v[2];
; #pragma unroll
;             for (int n = 0; n < 2; ++n)
; #pragma unroll
;                 for (int j = 0; j < 4; ++j) v[n][j] = silu(acc[ai][0][m][n][j] * r) * (acc[ai][1][m][n][j] * r);
;             *(u32x4*)(act + (size_t)row * FF + cb) = pack8(v[0], v[1]); }
	v_cvt_pk_bf16_f32 v96, v100, v101
	v_mad_i64_i32 v[100:101], s[38:39], v168, s49, v[112:113]
	v_cvt_pk_bf16_f32 v97, v102, v103
	v_cvt_pk_bf16_f32 v98, v104, v105
	v_cvt_pk_bf16_f32 v99, v106, v107
	v_lshl_add_u64 v[100:101], v[100:101], 0, v[114:115]
	v_mul_f32_e32 v102, 0xbfb8aa3b, v92
	v_mul_f32_e32 v103, 0xbfb8aa3b, v93
	v_pk_mul_f32 v[94:95], v[94:95], v[166:167] op_sel_hi:[1,0]
	v_exp_f32_e32 v102, v102
	v_exp_f32_e32 v103, v103
	global_store_dwordx4 v[100:101], v[96:99], off
	v_pk_mul_f32 v[84:85], v[84:85], v[166:167] op_sel_hi:[1,0]
	v_pk_mul_f32 v[88:89], v[88:89], v[166:167] op_sel_hi:[1,0]
	v_mul_f32_e32 v98, 0xbfb8aa3b, v94
	v_mul_f32_e32 v99, 0xbfb8aa3b, v95
	v_exp_f32_e32 v98, v98
	v_exp_f32_e32 v99, v99
	v_add_f32_e32 v96, 1.0, v102
	v_add_f32_e32 v97, 1.0, v103
	v_rcp_f32_e32 v96, v96
	v_rcp_f32_e32 v97, v97
	v_add_f32_e32 v98, 1.0, v98
	v_add_f32_e32 v99, 1.0, v99
	v_rcp_f32_e32 v98, v98
	v_rcp_f32_e32 v99, v99
	v_pk_mul_f32 v[92:93], v[92:93], v[96:97]
	v_pk_mul_f32 v[86:87], v[86:87], v[166:167] op_sel_hi:[1,0]
	v_pk_mul_f32 v[84:85], v[84:85], v[92:93]
	v_pk_mul_f32 v[92:93], v[94:95], v[98:99]
	v_mul_f32_e32 v94, 0xbfb8aa3b, v88
	v_mul_f32_e32 v95, 0xbfb8aa3b, v89
	v_exp_f32_e32 v94, v94
	v_exp_f32_e32 v95, v95
	v_pk_mul_f32 v[90:91], v[90:91], v[166:167] op_sel_hi:[1,0]
	v_pk_mul_f32 v[86:87], v[86:87], v[92:93]
	v_add_f32_e32 v92, 1.0, v94
	v_add_f32_e32 v93, 1.0, v95
	v_mul_f32_e32 v94, 0xbfb8aa3b, v90
	v_mul_f32_e32 v95, 0xbfb8aa3b, v91
	v_exp_f32_e32 v94, v94
	v_exp_f32_e32 v95, v95
	v_rcp_f32_e32 v92, v92
	v_rcp_f32_e32 v93, v93
	v_add_f32_e32 v94, 1.0, v94
	v_add_f32_e32 v95, 1.0, v95
	v_rcp_f32_e32 v94, v94
	v_rcp_f32_e32 v95, v95
	v_pk_mul_f32 v[88:89], v[88:89], v[92:93]
	v_pk_mul_f32 v[80:81], v[80:81], v[166:167] op_sel_hi:[1,0]
	v_pk_mul_f32 v[82:83], v[82:83], v[166:167] op_sel_hi:[1,0]
	v_pk_mul_f32 v[88:89], v[80:81], v[88:89]
	v_pk_mul_f32 v[80:81], v[90:91], v[94:95]
	v_pk_mul_f32 v[76:77], v[76:77], v[162:163] op_sel_hi:[1,0]
	v_pk_mul_f32 v[90:91], v[82:83], v[80:81]
	v_cvt_pk_bf16_f32 v80, v84, v85
	v_mad_i64_i32 v[84:85], s[38:39], v164, s49, v[112:113]
	v_cvt_pk_bf16_f32 v81, v86, v87
	v_cvt_pk_bf16_f32 v82, v88, v89
	v_cvt_pk_bf16_f32 v83, v90, v91
	v_lshl_add_u64 v[84:85], v[84:85], 0, v[114:115]
	v_mul_f32_e32 v86, 0xbfb8aa3b, v76
	v_mul_f32_e32 v87, 0xbfb8aa3b, v77
	v_pk_mul_f32 v[78:79], v[78:79], v[162:163] op_sel_hi:[1,0]
	v_exp_f32_e32 v86, v86
	v_exp_f32_e32 v87, v87
	global_store_dwordx4 v[84:85], v[80:83], off
	v_pk_mul_f32 v[68:69], v[68:69], v[162:163] op_sel_hi:[1,0]
	v_pk_mul_f32 v[72:73], v[72:73], v[162:163] op_sel_hi:[1,0]
	v_mul_f32_e32 v82, 0xbfb8aa3b, v78
	v_mul_f32_e32 v83, 0xbfb8aa3b, v79
	v_exp_f32_e32 v82, v82
	v_exp_f32_e32 v83, v83
	v_add_f32_e32 v80, 1.0, v86
	v_add_f32_e32 v81, 1.0, v87
	v_rcp_f32_e32 v80, v80
	v_rcp_f32_e32 v81, v81
	v_add_f32_e32 v82, 1.0, v82
	v_add_f32_e32 v83, 1.0, v83
	v_rcp_f32_e32 v82, v82
	v_rcp_f32_e32 v83, v83
	v_pk_mul_f32 v[76:77], v[76:77], v[80:81]
	v_pk_mul_f32 v[70:71], v[70:71], v[162:163] op_sel_hi:[1,0]
	v_pk_mul_f32 v[68:69], v[68:69], v[76:77]
	v_pk_mul_f32 v[76:77], v[78:79], v[82:83]
	v_mul_f32_e32 v78, 0xbfb8aa3b, v72
	v_mul_f32_e32 v79, 0xbfb8aa3b, v73
	v_exp_f32_e32 v78, v78
	v_exp_f32_e32 v79, v79
	v_pk_mul_f32 v[74:75], v[74:75], v[162:163] op_sel_hi:[1,0]
	v_pk_mul_f32 v[70:71], v[70:71], v[76:77]
	v_add_f32_e32 v76, 1.0, v78
	v_add_f32_e32 v77, 1.0, v79
	v_mul_f32_e32 v78, 0xbfb8aa3b, v74
	v_mul_f32_e32 v79, 0xbfb8aa3b, v75
	v_exp_f32_e32 v78, v78
	v_exp_f32_e32 v79, v79
	v_rcp_f32_e32 v76, v76
	v_rcp_f32_e32 v77, v77
	v_add_f32_e32 v78, 1.0, v78
	v_add_f32_e32 v79, 1.0, v79
	v_rcp_f32_e32 v78, v78
	v_rcp_f32_e32 v79, v79
	v_pk_mul_f32 v[72:73], v[72:73], v[76:77]
	v_pk_mul_f32 v[64:65], v[64:65], v[162:163] op_sel_hi:[1,0]
	v_pk_mul_f32 v[66:67], v[66:67], v[162:163] op_sel_hi:[1,0]
	v_pk_mul_f32 v[72:73], v[64:65], v[72:73]
	v_pk_mul_f32 v[64:65], v[74:75], v[78:79]
	v_pk_mul_f32 v[60:61], v[60:61], v[158:159] op_sel_hi:[1,0]
	v_pk_mul_f32 v[74:75], v[66:67], v[64:65]
	v_cvt_pk_bf16_f32 v64, v68, v69
	v_mad_i64_i32 v[68:69], s[38:39], v160, s49, v[112:113]
	v_cvt_pk_bf16_f32 v65, v70, v71
	v_cvt_pk_bf16_f32 v66, v72, v73
	v_cvt_pk_bf16_f32 v67, v74, v75
	v_lshl_add_u64 v[68:69], v[68:69], 0, v[114:115]
	v_mul_f32_e32 v70, 0xbfb8aa3b, v60
	v_mul_f32_e32 v71, 0xbfb8aa3b, v61
	v_pk_mul_f32 v[62:63], v[62:63], v[158:159] op_sel_hi:[1,0]
	v_exp_f32_e32 v70, v70
	v_exp_f32_e32 v71, v71
	global_store_dwordx4 v[68:69], v[64:67], off
	v_pk_mul_f32 v[52:53], v[52:53], v[158:159] op_sel_hi:[1,0]
	v_pk_mul_f32 v[56:57], v[56:57], v[158:159] op_sel_hi:[1,0]
	v_mul_f32_e32 v66, 0xbfb8aa3b, v62
	v_mul_f32_e32 v67, 0xbfb8aa3b, v63
	v_exp_f32_e32 v66, v66
	v_exp_f32_e32 v67, v67
	v_add_f32_e32 v64, 1.0, v70
	v_add_f32_e32 v65, 1.0, v71
	v_rcp_f32_e32 v64, v64
	v_rcp_f32_e32 v65, v65
	v_add_f32_e32 v66, 1.0, v66
	v_add_f32_e32 v67, 1.0, v67
	v_rcp_f32_e32 v66, v66
	v_rcp_f32_e32 v67, v67
	v_pk_mul_f32 v[60:61], v[60:61], v[64:65]
	v_pk_mul_f32 v[54:55], v[54:55], v[158:159] op_sel_hi:[1,0]
	v_pk_mul_f32 v[52:53], v[52:53], v[60:61]
	v_pk_mul_f32 v[60:61], v[62:63], v[66:67]
	v_mul_f32_e32 v62, 0xbfb8aa3b, v56
	v_mul_f32_e32 v63, 0xbfb8aa3b, v57
	v_exp_f32_e32 v62, v62
	v_exp_f32_e32 v63, v63
	v_pk_mul_f32 v[58:59], v[58:59], v[158:159] op_sel_hi:[1,0]
	v_pk_mul_f32 v[54:55], v[54:55], v[60:61]
	v_add_f32_e32 v60, 1.0, v62
	v_add_f32_e32 v61, 1.0, v63
	v_mul_f32_e32 v62, 0xbfb8aa3b, v58
	v_mul_f32_e32 v63, 0xbfb8aa3b, v59
	v_exp_f32_e32 v62, v62
	v_exp_f32_e32 v63, v63
	v_rcp_f32_e32 v60, v60
	v_rcp_f32_e32 v61, v61
; DI float silu(float x) { return x * sigm(x); }
; DI int lane_id() { int l; asm volatile("v_mbcnt_lo_u32_b32 %0, -1, 0\n\tv_mbcnt_hi_u32_b32 %0, -1, %0" : "=v"(l)); return l; }
; DI u32x4 pack8(f32x4 a, f32x4 b) { u32x4 w; w.x = pk2(a[0], a[1]); w.y = pk2(a[2], a[3]); w.z = pk2(b[0], b[1]); w.w = pk2(b[2], b[3]); return w; }
; #define PG8_BAR __builtin_amdgcn_s_barrier()
; #define EPI_ROWS(ai, m) _Pragma("unroll") for (int ai = 0; ai < 2; ++ai) _Pragma("unroll") for (int m = 0; m < 4; ++m)
; template <class Epi>
; DI void gemm_phase(LAS unsigned char* lds, const int wid, const Gemm g, const Order& S, const Epi& E) {
;     ...
;         if (wr == 0) PG8_BAR;
;         { const int le = lane_id(); E(acc, cur, wr, wc, le & 15, le >> 4); }
;         if (!has_next) break;
; #pragma unroll
;         for (int a = 0; a < 2; ++a)
; #pragma unroll
;             for (int b = 0; b < 2; ++b)
; #pragma unroll
;                 for (int m = 0; m < 4; ++m)
; #pragma unroll
;                     for (int n = 0; n < 2; ++n) acc[a][b][m][n] = (f32x4){0.f, 0.f, 0.f, 0.f};
;         cur = nxt; cA = nA; cB = nB; ++ui;
;         if (wr == 1) PG8_BAR;
;     DI void operator()(const Acc& acc, const Unit& u, int wr, int wc, int fr, int fq) const {
;     ...
;         EPI_ROWS(ai, m) { const int row = epi_row(u, ai, wr, m, fr); const float r = rr[ai][m];
;             f32x4 v[2];
; #pragma unroll
;             for (int n = 0; n < 2; ++n)
; #pragma unroll
;                 for (int j = 0; j < 4; ++j) v[n][j] = silu(acc[ai][0][m][n][j] * r) * (acc[ai][1][m][n][j] * r);
;             *(u32x4*)(act + (size_t)row * FF + cb) = pack8(v[0], v[1]); }
	v_add_f32_e32 v62, 1.0, v62
	v_add_f32_e32 v63, 1.0, v63
	v_rcp_f32_e32 v62, v62
	v_rcp_f32_e32 v63, v63
	v_pk_mul_f32 v[56:57], v[56:57], v[60:61]
	v_pk_mul_f32 v[48:49], v[48:49], v[158:159] op_sel_hi:[1,0]
	v_pk_mul_f32 v[50:51], v[50:51], v[158:159] op_sel_hi:[1,0]
	v_pk_mul_f32 v[56:57], v[48:49], v[56:57]
	v_pk_mul_f32 v[48:49], v[58:59], v[62:63]
	v_pk_mul_f32 v[44:45], v[44:45], v[154:155] op_sel_hi:[1,0]
	v_pk_mul_f32 v[58:59], v[50:51], v[48:49]
	v_cvt_pk_bf16_f32 v48, v52, v53
	v_mad_i64_i32 v[52:53], s[38:39], v156, s49, v[112:113]
	v_cvt_pk_bf16_f32 v49, v54, v55
	v_cvt_pk_bf16_f32 v50, v56, v57
	v_cvt_pk_bf16_f32 v51, v58, v59
	v_lshl_add_u64 v[52:53], v[52:53], 0, v[114:115]
	v_mul_f32_e32 v54, 0xbfb8aa3b, v44
	v_mul_f32_e32 v55, 0xbfb8aa3b, v45
	v_pk_mul_f32 v[46:47], v[46:47], v[154:155] op_sel_hi:[1,0]
	v_exp_f32_e32 v54, v54
	v_exp_f32_e32 v55, v55
	global_store_dwordx4 v[52:53], v[48:51], off
	v_pk_mul_f32 v[36:37], v[36:37], v[154:155] op_sel_hi:[1,0]
	v_pk_mul_f32 v[40:41], v[40:41], v[154:155] op_sel_hi:[1,0]
	v_mul_f32_e32 v50, 0xbfb8aa3b, v46
	v_mul_f32_e32 v51, 0xbfb8aa3b, v47
	v_exp_f32_e32 v50, v50
	v_exp_f32_e32 v51, v51
	v_add_f32_e32 v48, 1.0, v54
	v_add_f32_e32 v49, 1.0, v55
	v_rcp_f32_e32 v48, v48
	v_rcp_f32_e32 v49, v49
	v_add_f32_e32 v50, 1.0, v50
	v_add_f32_e32 v51, 1.0, v51
	v_rcp_f32_e32 v50, v50
	v_rcp_f32_e32 v51, v51
	v_pk_mul_f32 v[44:45], v[44:45], v[48:49]
	v_pk_mul_f32 v[38:39], v[38:39], v[154:155] op_sel_hi:[1,0]
	v_pk_mul_f32 v[36:37], v[36:37], v[44:45]
	v_pk_mul_f32 v[44:45], v[46:47], v[50:51]
	v_mul_f32_e32 v46, 0xbfb8aa3b, v40
	v_mul_f32_e32 v47, 0xbfb8aa3b, v41
	v_exp_f32_e32 v46, v46
	v_exp_f32_e32 v47, v47
	v_pk_mul_f32 v[42:43], v[42:43], v[154:155] op_sel_hi:[1,0]
	v_pk_mul_f32 v[38:39], v[38:39], v[44:45]
	v_add_f32_e32 v44, 1.0, v46
	v_add_f32_e32 v45, 1.0, v47
	v_mul_f32_e32 v46, 0xbfb8aa3b, v42
	v_mul_f32_e32 v47, 0xbfb8aa3b, v43
	v_exp_f32_e32 v46, v46
	v_exp_f32_e32 v47, v47
	v_rcp_f32_e32 v44, v44
	v_rcp_f32_e32 v45, v45
	v_add_f32_e32 v46, 1.0, v46
	v_add_f32_e32 v47, 1.0, v47
	v_rcp_f32_e32 v46, v46
	v_rcp_f32_e32 v47, v47
	v_pk_mul_f32 v[40:41], v[40:41], v[44:45]
	v_pk_mul_f32 v[32:33], v[32:33], v[154:155] op_sel_hi:[1,0]
	v_pk_mul_f32 v[34:35], v[34:35], v[154:155] op_sel_hi:[1,0]
	v_pk_mul_f32 v[40:41], v[32:33], v[40:41]
	v_pk_mul_f32 v[32:33], v[42:43], v[46:47]
	v_pk_mul_f32 v[28:29], v[28:29], v[150:151] op_sel_hi:[1,0]
	v_pk_mul_f32 v[42:43], v[34:35], v[32:33]
	v_cvt_pk_bf16_f32 v32, v36, v37
	v_mad_i64_i32 v[36:37], s[38:39], v152, s49, v[112:113]
	v_cvt_pk_bf16_f32 v33, v38, v39
	v_cvt_pk_bf16_f32 v34, v40, v41
	v_cvt_pk_bf16_f32 v35, v42, v43
	v_lshl_add_u64 v[36:37], v[36:37], 0, v[114:115]
	v_mul_f32_e32 v38, 0xbfb8aa3b, v28
	v_mul_f32_e32 v39, 0xbfb8aa3b, v29
	v_pk_mul_f32 v[30:31], v[30:31], v[150:151] op_sel_hi:[1,0]
	v_exp_f32_e32 v38, v38
	v_exp_f32_e32 v39, v39
	global_store_dwordx4 v[36:37], v[32:35], off
	v_pk_mul_f32 v[20:21], v[20:21], v[150:151] op_sel_hi:[1,0]
	v_pk_mul_f32 v[24:25], v[24:25], v[150:151] op_sel_hi:[1,0]
	v_mul_f32_e32 v34, 0xbfb8aa3b, v30
	v_mul_f32_e32 v35, 0xbfb8aa3b, v31
	v_exp_f32_e32 v34, v34
	v_exp_f32_e32 v35, v35
	v_add_f32_e32 v32, 1.0, v38
	v_add_f32_e32 v33, 1.0, v39
	v_rcp_f32_e32 v32, v32
	v_rcp_f32_e32 v33, v33
	v_add_f32_e32 v34, 1.0, v34
	v_add_f32_e32 v35, 1.0, v35
	v_rcp_f32_e32 v34, v34
	v_rcp_f32_e32 v35, v35
	v_pk_mul_f32 v[28:29], v[28:29], v[32:33]
	v_pk_mul_f32 v[22:23], v[22:23], v[150:151] op_sel_hi:[1,0]
	v_pk_mul_f32 v[20:21], v[20:21], v[28:29]
	v_pk_mul_f32 v[28:29], v[30:31], v[34:35]
	v_mul_f32_e32 v30, 0xbfb8aa3b, v24
	v_mul_f32_e32 v31, 0xbfb8aa3b, v25
	v_exp_f32_e32 v30, v30
	v_exp_f32_e32 v31, v31
	v_pk_mul_f32 v[26:27], v[26:27], v[150:151] op_sel_hi:[1,0]
	v_pk_mul_f32 v[22:23], v[22:23], v[28:29]
	v_add_f32_e32 v28, 1.0, v30
	v_add_f32_e32 v29, 1.0, v31
	v_mul_f32_e32 v30, 0xbfb8aa3b, v26
	v_mul_f32_e32 v31, 0xbfb8aa3b, v27
	v_exp_f32_e32 v30, v30
	v_exp_f32_e32 v31, v31
	v_rcp_f32_e32 v28, v28
	v_rcp_f32_e32 v29, v29
	v_add_f32_e32 v30, 1.0, v30
	v_add_f32_e32 v31, 1.0, v31
	v_rcp_f32_e32 v30, v30
	v_rcp_f32_e32 v31, v31
	v_pk_mul_f32 v[24:25], v[24:25], v[28:29]
	v_pk_mul_f32 v[16:17], v[16:17], v[150:151] op_sel_hi:[1,0]
	v_pk_mul_f32 v[18:19], v[18:19], v[150:151] op_sel_hi:[1,0]
	v_pk_mul_f32 v[24:25], v[16:17], v[24:25]
	v_pk_mul_f32 v[16:17], v[26:27], v[30:31]
	v_pk_mul_f32 v[12:13], v[12:13], v[146:147] op_sel_hi:[1,0]
	v_pk_mul_f32 v[26:27], v[18:19], v[16:17]
	v_cvt_pk_bf16_f32 v16, v20, v21
	v_mad_i64_i32 v[20:21], s[38:39], v148, s49, v[112:113]
	v_cvt_pk_bf16_f32 v17, v22, v23
	v_cvt_pk_bf16_f32 v18, v24, v25
	v_cvt_pk_bf16_f32 v19, v26, v27
	v_lshl_add_u64 v[20:21], v[20:21], 0, v[114:115]
	v_mul_f32_e32 v22, 0xbfb8aa3b, v12
	v_mul_f32_e32 v23, 0xbfb8aa3b, v13
	v_pk_mul_f32 v[14:15], v[14:15], v[146:147] op_sel_hi:[1,0]
	v_exp_f32_e32 v22, v22
	v_exp_f32_e32 v23, v23
	global_store_dwordx4 v[20:21], v[16:19], off
	v_pk_mul_f32 v[4:5], v[4:5], v[146:147] op_sel_hi:[1,0]
	v_pk_mul_f32 v[8:9], v[8:9], v[146:147] op_sel_hi:[1,0]
	v_mul_f32_e32 v18, 0xbfb8aa3b, v14
	v_mul_f32_e32 v19, 0xbfb8aa3b, v15
	v_exp_f32_e32 v18, v18
	v_exp_f32_e32 v19, v19
	v_add_f32_e32 v16, 1.0, v22
	v_add_f32_e32 v17, 1.0, v23
	v_rcp_f32_e32 v16, v16
	v_rcp_f32_e32 v17, v17
	v_add_f32_e32 v18, 1.0, v18
	v_add_f32_e32 v19, 1.0, v19
	v_rcp_f32_e32 v18, v18
	v_rcp_f32_e32 v19, v19
	v_pk_mul_f32 v[12:13], v[12:13], v[16:17]
	v_pk_mul_f32 v[6:7], v[6:7], v[146:147] op_sel_hi:[1,0]
	v_pk_mul_f32 v[4:5], v[4:5], v[12:13]
	v_pk_mul_f32 v[12:13], v[14:15], v[18:19]
	v_mul_f32_e32 v14, 0xbfb8aa3b, v8
	v_mul_f32_e32 v15, 0xbfb8aa3b, v9
	v_exp_f32_e32 v14, v14
	v_exp_f32_e32 v15, v15
	v_pk_mul_f32 v[10:11], v[10:11], v[146:147] op_sel_hi:[1,0]
	v_pk_mul_f32 v[6:7], v[6:7], v[12:13]
	v_add_f32_e32 v12, 1.0, v14
	v_add_f32_e32 v13, 1.0, v15
	v_mul_f32_e32 v14, 0xbfb8aa3b, v10
	v_mul_f32_e32 v15, 0xbfb8aa3b, v11
	v_exp_f32_e32 v14, v14
	v_exp_f32_e32 v15, v15
	v_rcp_f32_e32 v12, v12
	v_rcp_f32_e32 v13, v13
	v_add_f32_e32 v14, 1.0, v14
	v_add_f32_e32 v15, 1.0, v15
	v_rcp_f32_e32 v14, v14
	v_rcp_f32_e32 v15, v15
	v_pk_mul_f32 v[8:9], v[8:9], v[12:13]
	v_pk_mul_f32 v[0:1], v[0:1], v[146:147] op_sel_hi:[1,0]
	v_pk_mul_f32 v[2:3], v[2:3], v[146:147] op_sel_hi:[1,0]
	v_pk_mul_f32 v[8:9], v[0:1], v[8:9]
	v_pk_mul_f32 v[0:1], v[10:11], v[14:15]
	s_nop 0
	v_pk_mul_f32 v[10:11], v[2:3], v[0:1]
	v_cvt_pk_bf16_f32 v0, v4, v5
	v_mad_i64_i32 v[4:5], s[38:39], v144, s49, v[112:113]
	v_cvt_pk_bf16_f32 v1, v6, v7
	v_cvt_pk_bf16_f32 v2, v8, v9
	v_cvt_pk_bf16_f32 v3, v10, v11
	v_lshl_add_u64 v[4:5], v[4:5], 0, v[114:115]
	global_store_dwordx4 v[4:5], v[0:3], off
	s_cbranch_vccnz .LBB0_1332
	s_andn2_b64 vcc, exec, s[10:11]
	s_cbranch_vccnz .LBB0_1331
	s_barrier
	s_branch .LBB0_1331
